# v113 + GEMM K-loops: LDS-DMA loads use SGPR base + 32-bit VGPR offset instead of a 64-bit VALU address add (46 loads)
# speedup vs baseline: 1.0295x; 1.0020x over previous
.Lg1_peel:
	ds_read_b128 v[128:131], v175
	ds_read_b128 v[132:135], v175 offset:1024
	ds_read_b128 v[150:153], v175 offset:2048
	ds_read_b128 v[154:157], v175 offset:3072
	ds_read_b128 v[186:189], v177
	ds_read_b128 v[190:193], v177 offset:1024
	ds_read_b128 v[194:197], v177 offset:2048
	ds_read_b128 v[198:201], v177 offset:3072
	s_add_u32 s72, s4, 0xfffc0080
	s_addc_u32 s73, s5, -1
	s_cmp_eq_u32 s77, 12
	s_cselect_b32 s75, s15, s73
	s_cselect_b32 s74, s18, s72
	s_cselect_b32 s73, s45, s76
	s_cselect_b32 s72, s65, s67
	s_add_i32 m0, s17, 0xc000
	ds_read_b128 v[202:205], v179
	ds_read_b128 v[206:209], v179 offset:1024
	ds_read_b128 v[210:213], v179 offset:2048
	ds_read_b128 v[214:217], v179 offset:3072
	ds_read_b128 v[218:221], v179 offset:4096
	ds_read_b128 v[222:225], v179 offset:5120
	ds_read_b128 v[230:233], v179 offset:6144
	ds_read_b128 v[234:237], v179 offset:7168
	global_load_lds_dwordx4 v146, s[4:5]
	s_add_i32 m0, s17, 0xe000
	s_nop 0
	global_load_lds_dwordx4 v148, s[4:5]
	s_waitcnt lgkmcnt(0)
	s_barrier
	s_setprio 1
	s_waitcnt lgkmcnt(0)
	v_mfma_f32_16x16x32_bf16 v[124:127], v[128:131], v[202:205], 0
	v_mfma_f32_16x16x32_bf16 v[120:123], v[150:153], v[202:205], 0
	v_mfma_f32_16x16x32_bf16 v[108:111], v[128:131], v[210:213], 0
	v_mfma_f32_16x16x32_bf16 v[104:107], v[150:153], v[210:213], 0
	v_mfma_f32_16x16x32_bf16 v[92:95], v[128:131], v[218:221], 0
	v_mfma_f32_16x16x32_bf16 v[88:91], v[150:153], v[218:221], 0
	v_mfma_f32_16x16x32_bf16 v[76:79], v[128:131], v[230:233], 0
	v_mfma_f32_16x16x32_bf16 v[72:75], v[150:153], v[230:233], 0
	v_mfma_f32_16x16x32_bf16 v[124:127], v[132:135], v[206:209], v[124:127]
	v_mfma_f32_16x16x32_bf16 v[120:123], v[154:157], v[206:209], v[120:123]
	v_mfma_f32_16x16x32_bf16 v[108:111], v[132:135], v[214:217], v[108:111]
	v_mfma_f32_16x16x32_bf16 v[104:107], v[154:157], v[214:217], v[104:107]
	v_mfma_f32_16x16x32_bf16 v[92:95], v[132:135], v[222:225], v[92:95]
	v_mfma_f32_16x16x32_bf16 v[88:91], v[154:157], v[222:225], v[88:91]
	v_mfma_f32_16x16x32_bf16 v[76:79], v[132:135], v[234:237], v[76:79]
	v_mfma_f32_16x16x32_bf16 v[72:75], v[154:157], v[234:237], v[72:75]
	s_setprio 0
	s_setprio 1
	v_mfma_f32_16x16x32_bf16 v[116:119], v[186:189], v[202:205], 0
	v_mfma_f32_16x16x32_bf16 v[112:115], v[194:197], v[202:205], 0
	v_mfma_f32_16x16x32_bf16 v[100:103], v[186:189], v[210:213], 0
	v_mfma_f32_16x16x32_bf16 v[96:99], v[194:197], v[210:213], 0
	v_mfma_f32_16x16x32_bf16 v[84:87], v[186:189], v[218:221], 0
	v_mfma_f32_16x16x32_bf16 v[80:83], v[194:197], v[218:221], 0
	v_mfma_f32_16x16x32_bf16 v[68:71], v[186:189], v[230:233], 0
	v_mfma_f32_16x16x32_bf16 v[64:67], v[194:197], v[230:233], 0
	v_mfma_f32_16x16x32_bf16 v[116:119], v[190:193], v[206:209], v[116:119]
	v_mfma_f32_16x16x32_bf16 v[112:115], v[198:201], v[206:209], v[112:115]
	v_mfma_f32_16x16x32_bf16 v[100:103], v[190:193], v[214:217], v[100:103]
	v_mfma_f32_16x16x32_bf16 v[96:99], v[198:201], v[214:217], v[96:99]
	v_mfma_f32_16x16x32_bf16 v[84:87], v[190:193], v[222:225], v[84:87]
	v_mfma_f32_16x16x32_bf16 v[80:83], v[198:201], v[222:225], v[80:83]
	v_mfma_f32_16x16x32_bf16 v[68:71], v[190:193], v[234:237], v[68:71]
	v_mfma_f32_16x16x32_bf16 v[64:67], v[198:201], v[234:237], v[64:67]
	s_setprio 0
	s_barrier
	s_add_i32 vcc_lo, s30, s53
	v_lshl_add_u64 v[158:159], s[72:73], 0, v[138:139]
	s_mov_b32 m0, vcc_lo
	ds_read_b128 v[202:205], v179 offset:16384
	ds_read_b128 v[206:209], v179 offset:17408
	ds_read_b128 v[210:213], v179 offset:18432
	ds_read_b128 v[214:217], v179 offset:19456
	ds_read_b128 v[218:221], v179 offset:20480
	ds_read_b128 v[222:225], v179 offset:21504
	ds_read_b128 v[230:233], v179 offset:22528
	ds_read_b128 v[234:237], v179 offset:23552
	global_load_lds_dwordx4 v[158:159], off
	s_add_i32 m0, vcc_lo, 0x2000
	s_add_u32 vcc_lo, s72, 0x40000
	v_lshl_add_u64 v[180:181], s[72:73], 0, v[142:143]
	s_addc_u32 vcc_hi, s73, 0
	s_add_i32 s79, s31, s53
	global_load_lds_dwordx4 v[180:181], off
	s_mov_b32 m0, s79
	v_lshl_add_u64 v[238:239], s[74:75], 0, v[140:141]
	global_load_lds_dwordx4 v138, vcc
	s_add_i32 m0, s79, 0x2000
	s_nop 0
	global_load_lds_dwordx4 v142, vcc
	v_lshl_add_u64 v[226:227], s[74:75], 0, v[136:137]
	s_mov_b32 m0, s17
	s_nop 0
	global_load_lds_dwordx4 v[226:227], off
	s_mov_b32 m0, s81
	s_nop 0
	global_load_lds_dwordx4 v[238:239], off
	s_waitcnt lgkmcnt(0)
	s_barrier
	s_setprio 1
	s_waitcnt lgkmcnt(0)
	v_mfma_f32_16x16x32_bf16 v[60:63], v[128:131], v[202:205], 0
	v_mfma_f32_16x16x32_bf16 v[56:59], v[150:153], v[202:205], 0
	v_mfma_f32_16x16x32_bf16 v[44:47], v[128:131], v[210:213], 0
	v_mfma_f32_16x16x32_bf16 v[40:43], v[150:153], v[210:213], 0
	v_mfma_f32_16x16x32_bf16 v[28:31], v[128:131], v[218:221], 0
	v_mfma_f32_16x16x32_bf16 v[24:27], v[150:153], v[218:221], 0
	v_mfma_f32_16x16x32_bf16 v[12:15], v[128:131], v[230:233], 0
	v_mfma_f32_16x16x32_bf16 v[8:11], v[150:153], v[230:233], 0
	v_mfma_f32_16x16x32_bf16 v[60:63], v[132:135], v[206:209], v[60:63]
	v_mfma_f32_16x16x32_bf16 v[56:59], v[154:157], v[206:209], v[56:59]
	v_mfma_f32_16x16x32_bf16 v[44:47], v[132:135], v[214:217], v[44:47]
	v_mfma_f32_16x16x32_bf16 v[40:43], v[154:157], v[214:217], v[40:43]
	v_mfma_f32_16x16x32_bf16 v[28:31], v[132:135], v[222:225], v[28:31]
	v_mfma_f32_16x16x32_bf16 v[24:27], v[154:157], v[222:225], v[24:27]
	v_mfma_f32_16x16x32_bf16 v[12:15], v[132:135], v[234:237], v[12:15]
	v_mfma_f32_16x16x32_bf16 v[8:11], v[154:157], v[234:237], v[8:11]
	s_setprio 0
	s_setprio 1
	v_mfma_f32_16x16x32_bf16 v[52:55], v[186:189], v[202:205], 0
	v_mfma_f32_16x16x32_bf16 v[48:51], v[194:197], v[202:205], 0
	v_mfma_f32_16x16x32_bf16 v[36:39], v[186:189], v[210:213], 0
	v_mfma_f32_16x16x32_bf16 v[32:35], v[194:197], v[210:213], 0
	v_mfma_f32_16x16x32_bf16 v[20:23], v[186:189], v[218:221], 0
	v_mfma_f32_16x16x32_bf16 v[16:19], v[194:197], v[218:221], 0
	v_mfma_f32_16x16x32_bf16 v[4:7], v[186:189], v[230:233], 0
	v_mfma_f32_16x16x32_bf16 v[0:3], v[194:197], v[230:233], 0
	v_mfma_f32_16x16x32_bf16 v[52:55], v[190:193], v[206:209], v[52:55]
	v_mfma_f32_16x16x32_bf16 v[48:51], v[198:201], v[206:209], v[48:51]
	v_mfma_f32_16x16x32_bf16 v[36:39], v[190:193], v[214:217], v[36:39]
	v_mfma_f32_16x16x32_bf16 v[32:35], v[198:201], v[214:217], v[32:35]
	v_mfma_f32_16x16x32_bf16 v[20:23], v[190:193], v[222:225], v[20:23]
	v_mfma_f32_16x16x32_bf16 v[16:19], v[198:201], v[222:225], v[16:19]
	v_mfma_f32_16x16x32_bf16 v[4:7], v[190:193], v[234:237], v[4:7]
	v_mfma_f32_16x16x32_bf16 v[0:3], v[198:201], v[234:237], v[0:3]
	s_setprio 0
	s_barrier
	s_branch .Lg1_mid
.LBB0_213:
	ds_read_b128 v[128:131], v175
	ds_read_b128 v[132:135], v175 offset:1024
	ds_read_b128 v[150:153], v175 offset:2048
	ds_read_b128 v[154:157], v175 offset:3072
	ds_read_b128 v[186:189], v177
	ds_read_b128 v[190:193], v177 offset:1024
	ds_read_b128 v[194:197], v177 offset:2048
	ds_read_b128 v[198:201], v177 offset:3072
	s_add_u32 s72, s4, 0xfffc0080
	s_addc_u32 s73, s5, -1
	s_cmp_eq_u32 s77, 12
	s_cselect_b32 s75, s15, s73
	s_cselect_b32 s74, s18, s72
	s_cselect_b32 s73, s45, s76
	s_cselect_b32 s72, s65, s67
	s_add_i32 m0, s17, 0xc000
	ds_read_b128 v[202:205], v179
	ds_read_b128 v[206:209], v179 offset:1024
	ds_read_b128 v[210:213], v179 offset:2048
	ds_read_b128 v[214:217], v179 offset:3072
	ds_read_b128 v[218:221], v179 offset:4096
	ds_read_b128 v[222:225], v179 offset:5120
	ds_read_b128 v[230:233], v179 offset:6144
	ds_read_b128 v[234:237], v179 offset:7168
	global_load_lds_dwordx4 v146, s[4:5]
	s_add_i32 m0, s17, 0xe000
	s_nop 0
	global_load_lds_dwordx4 v148, s[4:5]
	s_waitcnt vmcnt(8)
	s_waitcnt lgkmcnt(0)
	s_barrier
	s_setprio 1
	s_waitcnt lgkmcnt(0)
	v_mfma_f32_16x16x32_bf16 v[124:127], v[128:131], v[202:205], v[124:127]
	v_mfma_f32_16x16x32_bf16 v[120:123], v[150:153], v[202:205], v[120:123]
	v_mfma_f32_16x16x32_bf16 v[108:111], v[128:131], v[210:213], v[108:111]
	v_mfma_f32_16x16x32_bf16 v[104:107], v[150:153], v[210:213], v[104:107]
	v_mfma_f32_16x16x32_bf16 v[92:95], v[128:131], v[218:221], v[92:95]
	v_mfma_f32_16x16x32_bf16 v[88:91], v[150:153], v[218:221], v[88:91]
	v_mfma_f32_16x16x32_bf16 v[76:79], v[128:131], v[230:233], v[76:79]
	v_mfma_f32_16x16x32_bf16 v[72:75], v[150:153], v[230:233], v[72:75]
	v_mfma_f32_16x16x32_bf16 v[124:127], v[132:135], v[206:209], v[124:127]
	v_mfma_f32_16x16x32_bf16 v[120:123], v[154:157], v[206:209], v[120:123]
	v_mfma_f32_16x16x32_bf16 v[108:111], v[132:135], v[214:217], v[108:111]
	v_mfma_f32_16x16x32_bf16 v[104:107], v[154:157], v[214:217], v[104:107]
	v_mfma_f32_16x16x32_bf16 v[92:95], v[132:135], v[222:225], v[92:95]
	v_mfma_f32_16x16x32_bf16 v[88:91], v[154:157], v[222:225], v[88:91]
	v_mfma_f32_16x16x32_bf16 v[76:79], v[132:135], v[234:237], v[76:79]
	v_mfma_f32_16x16x32_bf16 v[72:75], v[154:157], v[234:237], v[72:75]
	s_setprio 0
	s_setprio 1
	v_mfma_f32_16x16x32_bf16 v[116:119], v[186:189], v[202:205], v[116:119]
	v_mfma_f32_16x16x32_bf16 v[112:115], v[194:197], v[202:205], v[112:115]
	v_mfma_f32_16x16x32_bf16 v[100:103], v[186:189], v[210:213], v[100:103]
	v_mfma_f32_16x16x32_bf16 v[96:99], v[194:197], v[210:213], v[96:99]
	v_mfma_f32_16x16x32_bf16 v[84:87], v[186:189], v[218:221], v[84:87]
	v_mfma_f32_16x16x32_bf16 v[80:83], v[194:197], v[218:221], v[80:83]
	v_mfma_f32_16x16x32_bf16 v[68:71], v[186:189], v[230:233], v[68:71]
	v_mfma_f32_16x16x32_bf16 v[64:67], v[194:197], v[230:233], v[64:67]
	v_mfma_f32_16x16x32_bf16 v[116:119], v[190:193], v[206:209], v[116:119]
	v_mfma_f32_16x16x32_bf16 v[112:115], v[198:201], v[206:209], v[112:115]
	v_mfma_f32_16x16x32_bf16 v[100:103], v[190:193], v[214:217], v[100:103]
	v_mfma_f32_16x16x32_bf16 v[96:99], v[198:201], v[214:217], v[96:99]
	v_mfma_f32_16x16x32_bf16 v[84:87], v[190:193], v[222:225], v[84:87]
	v_mfma_f32_16x16x32_bf16 v[80:83], v[198:201], v[222:225], v[80:83]
	v_mfma_f32_16x16x32_bf16 v[68:71], v[190:193], v[234:237], v[68:71]
	v_mfma_f32_16x16x32_bf16 v[64:67], v[198:201], v[234:237], v[64:67]
	s_setprio 0
	s_barrier
	s_add_i32 vcc_lo, s30, s53
	v_lshl_add_u64 v[158:159], s[72:73], 0, v[138:139]
	s_mov_b32 m0, vcc_lo
	ds_read_b128 v[202:205], v179 offset:16384
	ds_read_b128 v[206:209], v179 offset:17408
	ds_read_b128 v[210:213], v179 offset:18432
	ds_read_b128 v[214:217], v179 offset:19456
	ds_read_b128 v[218:221], v179 offset:20480
	ds_read_b128 v[222:225], v179 offset:21504
	ds_read_b128 v[230:233], v179 offset:22528
	ds_read_b128 v[234:237], v179 offset:23552
	global_load_lds_dwordx4 v[158:159], off
	s_add_i32 m0, vcc_lo, 0x2000
	s_add_u32 vcc_lo, s72, 0x40000
	v_lshl_add_u64 v[180:181], s[72:73], 0, v[142:143]
	s_addc_u32 vcc_hi, s73, 0
	s_add_i32 s79, s31, s53
	global_load_lds_dwordx4 v[180:181], off
	s_mov_b32 m0, s79
	v_lshl_add_u64 v[238:239], s[74:75], 0, v[140:141]
	global_load_lds_dwordx4 v138, vcc
	s_add_i32 m0, s79, 0x2000
	s_nop 0
	global_load_lds_dwordx4 v142, vcc
	v_lshl_add_u64 v[226:227], s[74:75], 0, v[136:137]
	s_mov_b32 m0, s17
	s_nop 0
	global_load_lds_dwordx4 v[226:227], off
	s_mov_b32 m0, s81
	s_nop 0
	global_load_lds_dwordx4 v[238:239], off
	s_waitcnt vmcnt(8)
	s_waitcnt lgkmcnt(0)
	s_barrier
	s_setprio 1
	s_waitcnt lgkmcnt(0)
	v_mfma_f32_16x16x32_bf16 v[60:63], v[128:131], v[202:205], v[60:63]
	v_mfma_f32_16x16x32_bf16 v[56:59], v[150:153], v[202:205], v[56:59]
	v_mfma_f32_16x16x32_bf16 v[44:47], v[128:131], v[210:213], v[44:47]
	v_mfma_f32_16x16x32_bf16 v[40:43], v[150:153], v[210:213], v[40:43]
	v_mfma_f32_16x16x32_bf16 v[28:31], v[128:131], v[218:221], v[28:31]
	v_mfma_f32_16x16x32_bf16 v[24:27], v[150:153], v[218:221], v[24:27]
	v_mfma_f32_16x16x32_bf16 v[12:15], v[128:131], v[230:233], v[12:15]
	v_mfma_f32_16x16x32_bf16 v[8:11], v[150:153], v[230:233], v[8:11]
	v_mfma_f32_16x16x32_bf16 v[60:63], v[132:135], v[206:209], v[60:63]
	v_mfma_f32_16x16x32_bf16 v[56:59], v[154:157], v[206:209], v[56:59]
	v_mfma_f32_16x16x32_bf16 v[44:47], v[132:135], v[214:217], v[44:47]
	v_mfma_f32_16x16x32_bf16 v[40:43], v[154:157], v[214:217], v[40:43]
	v_mfma_f32_16x16x32_bf16 v[28:31], v[132:135], v[222:225], v[28:31]
	v_mfma_f32_16x16x32_bf16 v[24:27], v[154:157], v[222:225], v[24:27]
	v_mfma_f32_16x16x32_bf16 v[12:15], v[132:135], v[234:237], v[12:15]
	v_mfma_f32_16x16x32_bf16 v[8:11], v[154:157], v[234:237], v[8:11]
	s_setprio 0
	s_setprio 1
	v_mfma_f32_16x16x32_bf16 v[52:55], v[186:189], v[202:205], v[52:55]
	v_mfma_f32_16x16x32_bf16 v[48:51], v[194:197], v[202:205], v[48:51]
	v_mfma_f32_16x16x32_bf16 v[36:39], v[186:189], v[210:213], v[36:39]
	v_mfma_f32_16x16x32_bf16 v[32:35], v[194:197], v[210:213], v[32:35]
	v_mfma_f32_16x16x32_bf16 v[20:23], v[186:189], v[218:221], v[20:23]
	v_mfma_f32_16x16x32_bf16 v[16:19], v[194:197], v[218:221], v[16:19]
	v_mfma_f32_16x16x32_bf16 v[4:7], v[186:189], v[230:233], v[4:7]
	v_mfma_f32_16x16x32_bf16 v[0:3], v[194:197], v[230:233], v[0:3]
	v_mfma_f32_16x16x32_bf16 v[52:55], v[190:193], v[206:209], v[52:55]
	v_mfma_f32_16x16x32_bf16 v[48:51], v[198:201], v[206:209], v[48:51]
	v_mfma_f32_16x16x32_bf16 v[36:39], v[190:193], v[214:217], v[36:39]
	v_mfma_f32_16x16x32_bf16 v[32:35], v[198:201], v[214:217], v[32:35]
	v_mfma_f32_16x16x32_bf16 v[20:23], v[190:193], v[222:225], v[20:23]
	v_mfma_f32_16x16x32_bf16 v[16:19], v[198:201], v[222:225], v[16:19]
	v_mfma_f32_16x16x32_bf16 v[4:7], v[190:193], v[234:237], v[4:7]
	v_mfma_f32_16x16x32_bf16 v[0:3], v[198:201], v[234:237], v[0:3]
	s_setprio 0
	s_barrier
.Lg1_mid:
	s_add_i32 s79, 0, 0x18000
	v_add_u32_e32 v144, s79, v161
	s_add_i32 vcc_lo, 0, 0x1c000
	ds_read_b128 v[128:131], v144
	ds_read_b128 v[132:135], v144 offset:1024
	ds_read_b128 v[150:153], v144 offset:2048
	ds_read_b128 v[154:157], v144 offset:3072
	v_add_u32_e32 v144, vcc_lo, v161
	ds_read_b128 v[186:189], v144
	ds_read_b128 v[190:193], v144 offset:1024
	ds_read_b128 v[194:197], v144 offset:2048
	ds_read_b128 v[198:201], v144 offset:3072
	s_add_u32 s74, s74, 0x40000
	s_addc_u32 s75, s75, 0
	s_mov_b32 m0, s82
	ds_read_b128 v[202:205], v179 offset:32768
	ds_read_b128 v[206:209], v179 offset:33792
	ds_read_b128 v[210:213], v179 offset:34816
	ds_read_b128 v[214:217], v179 offset:35840
	ds_read_b128 v[218:221], v179 offset:36864
	ds_read_b128 v[222:225], v179 offset:37888
	ds_read_b128 v[230:233], v179 offset:38912
	ds_read_b128 v[234:237], v179 offset:39936
	global_load_lds_dwordx4 v136, s[74:75]
	s_mov_b32 m0, s83
	s_nop 0
	global_load_lds_dwordx4 v140, s[74:75]
	s_waitcnt vmcnt(8)
	s_waitcnt lgkmcnt(0)
	s_barrier
	s_setprio 1
	s_waitcnt lgkmcnt(0)
	v_mfma_f32_16x16x32_bf16 v[124:127], v[128:131], v[202:205], v[124:127]
	v_mfma_f32_16x16x32_bf16 v[120:123], v[150:153], v[202:205], v[120:123]
	v_mfma_f32_16x16x32_bf16 v[108:111], v[128:131], v[210:213], v[108:111]
	v_mfma_f32_16x16x32_bf16 v[104:107], v[150:153], v[210:213], v[104:107]
	v_mfma_f32_16x16x32_bf16 v[92:95], v[128:131], v[218:221], v[92:95]
	v_mfma_f32_16x16x32_bf16 v[88:91], v[150:153], v[218:221], v[88:91]
	v_mfma_f32_16x16x32_bf16 v[76:79], v[128:131], v[230:233], v[76:79]
	v_mfma_f32_16x16x32_bf16 v[72:75], v[150:153], v[230:233], v[72:75]
	v_mfma_f32_16x16x32_bf16 v[124:127], v[132:135], v[206:209], v[124:127]
	v_mfma_f32_16x16x32_bf16 v[120:123], v[154:157], v[206:209], v[120:123]
	v_mfma_f32_16x16x32_bf16 v[108:111], v[132:135], v[214:217], v[108:111]
	v_mfma_f32_16x16x32_bf16 v[104:107], v[154:157], v[214:217], v[104:107]
	v_mfma_f32_16x16x32_bf16 v[92:95], v[132:135], v[222:225], v[92:95]
	v_mfma_f32_16x16x32_bf16 v[88:91], v[154:157], v[222:225], v[88:91]
	v_mfma_f32_16x16x32_bf16 v[76:79], v[132:135], v[234:237], v[76:79]
	v_mfma_f32_16x16x32_bf16 v[72:75], v[154:157], v[234:237], v[72:75]
	s_setprio 0
	s_setprio 1
	v_mfma_f32_16x16x32_bf16 v[116:119], v[186:189], v[202:205], v[116:119]
	v_mfma_f32_16x16x32_bf16 v[112:115], v[194:197], v[202:205], v[112:115]
	v_mfma_f32_16x16x32_bf16 v[100:103], v[186:189], v[210:213], v[100:103]
	v_mfma_f32_16x16x32_bf16 v[96:99], v[194:197], v[210:213], v[96:99]
	v_mfma_f32_16x16x32_bf16 v[84:87], v[186:189], v[218:221], v[84:87]
	v_mfma_f32_16x16x32_bf16 v[80:83], v[194:197], v[218:221], v[80:83]
	v_mfma_f32_16x16x32_bf16 v[68:71], v[186:189], v[230:233], v[68:71]
	v_mfma_f32_16x16x32_bf16 v[64:67], v[194:197], v[230:233], v[64:67]
	v_mfma_f32_16x16x32_bf16 v[116:119], v[190:193], v[206:209], v[116:119]
	v_mfma_f32_16x16x32_bf16 v[112:115], v[198:201], v[206:209], v[112:115]
	v_mfma_f32_16x16x32_bf16 v[100:103], v[190:193], v[214:217], v[100:103]
	v_mfma_f32_16x16x32_bf16 v[96:99], v[198:201], v[214:217], v[96:99]
	v_mfma_f32_16x16x32_bf16 v[84:87], v[190:193], v[222:225], v[84:87]
	v_mfma_f32_16x16x32_bf16 v[80:83], v[198:201], v[222:225], v[80:83]
	v_mfma_f32_16x16x32_bf16 v[68:71], v[190:193], v[234:237], v[68:71]
	v_mfma_f32_16x16x32_bf16 v[64:67], v[198:201], v[234:237], v[64:67]
	s_setprio 0
	s_barrier
	s_add_i32 s74, s79, s53
	v_lshl_add_u64 v[158:159], v[158:159], 0, s[24:25]
	s_mov_b32 m0, s74
	ds_read_b128 v[202:205], v179 offset:49152
	ds_read_b128 v[206:209], v179 offset:50176
	ds_read_b128 v[210:213], v179 offset:51200
	ds_read_b128 v[214:217], v179 offset:52224
	ds_read_b128 v[218:221], v179 offset:53248
	ds_read_b128 v[222:225], v179 offset:54272
	ds_read_b128 v[230:233], v179 offset:55296
	ds_read_b128 v[234:237], v179 offset:56320
	global_load_lds_dwordx4 v[158:159], off
	s_add_i32 m0, s74, 0x2000
	s_add_u32 s72, s72, 0x40080
	v_lshl_add_u64 v[158:159], v[180:181], 0, s[24:25]
	s_addc_u32 s73, s73, 0
	s_add_i32 s74, vcc_lo, s53
	global_load_lds_dwordx4 v[158:159], off
	s_mov_b32 m0, s74
	s_nop 0
	global_load_lds_dwordx4 v138, s[72:73]
	s_add_i32 m0, s74, 0x2000
	s_nop 0
	global_load_lds_dwordx4 v142, s[72:73]
	v_lshl_add_u64 v[158:159], v[226:227], 0, s[24:25]
	s_mov_b32 m0, s86
	s_nop 0
	global_load_lds_dwordx4 v[158:159], off
	v_lshl_add_u64 v[158:159], v[238:239], 0, s[24:25]
	s_mov_b32 m0, s87
	s_nop 0
	global_load_lds_dwordx4 v[158:159], off
	s_waitcnt vmcnt(8)
	s_waitcnt lgkmcnt(0)
	s_barrier
	s_setprio 1
	s_waitcnt lgkmcnt(0)
	v_mfma_f32_16x16x32_bf16 v[60:63], v[128:131], v[202:205], v[60:63]
	v_mfma_f32_16x16x32_bf16 v[56:59], v[150:153], v[202:205], v[56:59]
	v_mfma_f32_16x16x32_bf16 v[44:47], v[128:131], v[210:213], v[44:47]
	v_mfma_f32_16x16x32_bf16 v[40:43], v[150:153], v[210:213], v[40:43]
	v_mfma_f32_16x16x32_bf16 v[28:31], v[128:131], v[218:221], v[28:31]
	v_mfma_f32_16x16x32_bf16 v[24:27], v[150:153], v[218:221], v[24:27]
	v_mfma_f32_16x16x32_bf16 v[12:15], v[128:131], v[230:233], v[12:15]
	v_mfma_f32_16x16x32_bf16 v[8:11], v[150:153], v[230:233], v[8:11]
	v_mfma_f32_16x16x32_bf16 v[60:63], v[132:135], v[206:209], v[60:63]
	v_mfma_f32_16x16x32_bf16 v[56:59], v[154:157], v[206:209], v[56:59]
	v_mfma_f32_16x16x32_bf16 v[44:47], v[132:135], v[214:217], v[44:47]
	v_mfma_f32_16x16x32_bf16 v[40:43], v[154:157], v[214:217], v[40:43]
	v_mfma_f32_16x16x32_bf16 v[28:31], v[132:135], v[222:225], v[28:31]
	v_mfma_f32_16x16x32_bf16 v[24:27], v[154:157], v[222:225], v[24:27]
	v_mfma_f32_16x16x32_bf16 v[12:15], v[132:135], v[234:237], v[12:15]
	v_mfma_f32_16x16x32_bf16 v[8:11], v[154:157], v[234:237], v[8:11]
	s_setprio 0
	s_setprio 1
	v_mfma_f32_16x16x32_bf16 v[52:55], v[186:189], v[202:205], v[52:55]
	v_mfma_f32_16x16x32_bf16 v[48:51], v[194:197], v[202:205], v[48:51]
	v_mfma_f32_16x16x32_bf16 v[36:39], v[186:189], v[210:213], v[36:39]
	v_mfma_f32_16x16x32_bf16 v[32:35], v[194:197], v[210:213], v[32:35]
	v_mfma_f32_16x16x32_bf16 v[20:23], v[186:189], v[218:221], v[20:23]
	v_mfma_f32_16x16x32_bf16 v[16:19], v[194:197], v[218:221], v[16:19]
	v_mfma_f32_16x16x32_bf16 v[4:7], v[186:189], v[230:233], v[4:7]
	v_mfma_f32_16x16x32_bf16 v[0:3], v[194:197], v[230:233], v[0:3]
	v_mfma_f32_16x16x32_bf16 v[52:55], v[190:193], v[206:209], v[52:55]
	v_mfma_f32_16x16x32_bf16 v[48:51], v[198:201], v[206:209], v[48:51]
	v_mfma_f32_16x16x32_bf16 v[36:39], v[190:193], v[214:217], v[36:39]
	v_mfma_f32_16x16x32_bf16 v[32:35], v[198:201], v[214:217], v[32:35]
	v_mfma_f32_16x16x32_bf16 v[20:23], v[190:193], v[222:225], v[20:23]
	v_mfma_f32_16x16x32_bf16 v[16:19], v[198:201], v[222:225], v[16:19]
	v_mfma_f32_16x16x32_bf16 v[4:7], v[190:193], v[234:237], v[4:7]
	v_mfma_f32_16x16x32_bf16 v[0:3], v[198:201], v[234:237], v[0:3]
	s_setprio 0
	s_barrier
	s_add_i32 s77, s77, 2
	s_add_u32 s4, s4, 0x100
	s_addc_u32 s5, s5, 0
	s_add_u32 s67, s67, 0x100
	s_addc_u32 s76, s76, 0
	s_cmp_gt_u32 s77, 13
	s_cbranch_scc0 .LBB0_213
	s_and_b64 vcc, exec, s[34:35]
	s_cbranch_vccz .LBB0_216
	s_barrier

.LBB0_1034:
	v_add_u32_e32 v1, s70, v204
	ds_read_b128 v[164:167], v1
	ds_read_b128 v[168:171], v1 offset:1024
	ds_read_b128 v[172:175], v1 offset:2048
	ds_read_b128 v[176:179], v1 offset:3072
	v_add_u32_e32 v1, s71, v204
	ds_read_b128 v[180:183], v1
	ds_read_b128 v[184:187], v1 offset:1024
	ds_read_b128 v[188:191], v1 offset:2048
	ds_read_b128 v[206:209], v1 offset:3072
	s_add_u32 s54, s4, 0xfffc0080
	s_addc_u32 s55, s5, -1
	s_cmp_eq_u32 s83, 12
	s_cselect_b32 s57, s31, s55
	s_cselect_b32 s56, s79, s54
	s_cselect_b32 s55, s35, s82
	s_cselect_b32 s54, s80, s81
	s_add_i32 m0, s53, 0xc000
	ds_read_b128 v[210:213], v205
	ds_read_b128 v[214:217], v205 offset:1024
	ds_read_b128 v[218:221], v205 offset:2048
	ds_read_b128 v[222:225], v205 offset:3072
	ds_read_b128 v[230:233], v205 offset:4096
	ds_read_b128 v[234:237], v205 offset:5120
	ds_read_b128 v[238:241], v205 offset:6144
	ds_read_b128 v[242:245], v205 offset:7168
	global_load_lds_dwordx4 v200, s[4:5]
	s_add_i32 m0, s53, 0xe000
	s_nop 0
	global_load_lds_dwordx4 v202, s[4:5]
	s_waitcnt vmcnt(8)
	s_waitcnt lgkmcnt(0)
	s_barrier
	s_setprio 1
	s_waitcnt lgkmcnt(0)
	v_mfma_f32_16x16x32_bf16 v[160:163], v[164:167], v[210:213], v[160:163]
	v_mfma_f32_16x16x32_bf16 v[156:159], v[172:175], v[210:213], v[156:159]
	v_mfma_f32_16x16x32_bf16 v[152:155], v[164:167], v[218:221], v[152:155]
	v_mfma_f32_16x16x32_bf16 v[148:151], v[172:175], v[218:221], v[148:151]
	v_mfma_f32_16x16x32_bf16 v[144:147], v[164:167], v[230:233], v[144:147]
	v_mfma_f32_16x16x32_bf16 v[140:143], v[172:175], v[230:233], v[140:143]
	v_mfma_f32_16x16x32_bf16 v[136:139], v[164:167], v[238:241], v[136:139]
	v_mfma_f32_16x16x32_bf16 v[132:135], v[172:175], v[238:241], v[132:135]
	v_mfma_f32_16x16x32_bf16 v[160:163], v[168:171], v[214:217], v[160:163]
	v_mfma_f32_16x16x32_bf16 v[156:159], v[176:179], v[214:217], v[156:159]
	v_mfma_f32_16x16x32_bf16 v[152:155], v[168:171], v[222:225], v[152:155]
	v_mfma_f32_16x16x32_bf16 v[148:151], v[176:179], v[222:225], v[148:151]
	v_mfma_f32_16x16x32_bf16 v[144:147], v[168:171], v[234:237], v[144:147]
	v_mfma_f32_16x16x32_bf16 v[140:143], v[176:179], v[234:237], v[140:143]
	v_mfma_f32_16x16x32_bf16 v[136:139], v[168:171], v[242:245], v[136:139]
	v_mfma_f32_16x16x32_bf16 v[132:135], v[176:179], v[242:245], v[132:135]
	s_setprio 0
	s_setprio 1
	v_mfma_f32_16x16x32_bf16 v[128:131], v[180:183], v[210:213], v[128:131]
	v_mfma_f32_16x16x32_bf16 v[124:127], v[188:191], v[210:213], v[124:127]
	v_mfma_f32_16x16x32_bf16 v[120:123], v[180:183], v[218:221], v[120:123]
	v_mfma_f32_16x16x32_bf16 v[116:119], v[188:191], v[218:221], v[116:119]
	v_mfma_f32_16x16x32_bf16 v[112:115], v[180:183], v[230:233], v[112:115]
	v_mfma_f32_16x16x32_bf16 v[108:111], v[188:191], v[230:233], v[108:111]
	v_mfma_f32_16x16x32_bf16 v[104:107], v[180:183], v[238:241], v[104:107]
	v_mfma_f32_16x16x32_bf16 v[100:103], v[188:191], v[238:241], v[100:103]
	v_mfma_f32_16x16x32_bf16 v[128:131], v[184:187], v[214:217], v[128:131]
	v_mfma_f32_16x16x32_bf16 v[124:127], v[206:209], v[214:217], v[124:127]
	v_mfma_f32_16x16x32_bf16 v[120:123], v[184:187], v[222:225], v[120:123]
	v_mfma_f32_16x16x32_bf16 v[116:119], v[206:209], v[222:225], v[116:119]
	v_mfma_f32_16x16x32_bf16 v[112:115], v[184:187], v[234:237], v[112:115]
	v_mfma_f32_16x16x32_bf16 v[108:111], v[206:209], v[234:237], v[108:111]
	v_mfma_f32_16x16x32_bf16 v[104:107], v[184:187], v[242:245], v[104:107]
	v_mfma_f32_16x16x32_bf16 v[100:103], v[206:209], v[242:245], v[100:103]
	s_setprio 0
	s_barrier
	s_add_i32 s84, s70, s44
	v_lshl_add_u64 v[2:3], s[54:55], 0, v[196:197]
	s_mov_b32 m0, s84
	ds_read_b128 v[210:213], v205 offset:16384
	ds_read_b128 v[214:217], v205 offset:17408
	ds_read_b128 v[218:221], v205 offset:18432
	ds_read_b128 v[222:225], v205 offset:19456
	ds_read_b128 v[230:233], v205 offset:20480
	ds_read_b128 v[234:237], v205 offset:21504
	ds_read_b128 v[238:241], v205 offset:22528
	ds_read_b128 v[242:245], v205 offset:23552
	global_load_lds_dwordx4 v[2:3], off
	s_add_i32 m0, s84, 0x2000
	s_add_u32 s84, s54, 0x40000
	v_lshl_add_u64 v[226:227], s[54:55], 0, v[192:193]
	s_addc_u32 s85, s55, 0
	s_add_i32 s86, s71, s44
	global_load_lds_dwordx4 v[226:227], off
	s_mov_b32 m0, s86
	v_lshl_add_u64 v[248:249], s[56:57], 0, v[194:195]
	global_load_lds_dwordx4 v196, s[84:85]
	s_add_i32 m0, s86, 0x2000
	s_nop 0
	global_load_lds_dwordx4 v192, s[84:85]
	v_lshl_add_u64 v[246:247], s[56:57], 0, v[198:199]
	s_mov_b32 m0, s53
	s_nop 0
	global_load_lds_dwordx4 v[246:247], off
	s_mov_b32 m0, s61
	s_nop 0
	global_load_lds_dwordx4 v[248:249], off
	s_waitcnt vmcnt(8)
	s_waitcnt lgkmcnt(0)
	s_barrier
	s_setprio 1
	s_waitcnt lgkmcnt(0)
	v_mfma_f32_16x16x32_bf16 v[96:99], v[164:167], v[210:213], v[96:99]
	v_mfma_f32_16x16x32_bf16 v[92:95], v[172:175], v[210:213], v[92:95]
	v_mfma_f32_16x16x32_bf16 v[88:91], v[164:167], v[218:221], v[88:91]
	v_mfma_f32_16x16x32_bf16 v[84:87], v[172:175], v[218:221], v[84:87]
	v_mfma_f32_16x16x32_bf16 v[80:83], v[164:167], v[230:233], v[80:83]
	v_mfma_f32_16x16x32_bf16 v[76:79], v[172:175], v[230:233], v[76:79]
	v_mfma_f32_16x16x32_bf16 v[72:75], v[164:167], v[238:241], v[72:75]
	v_mfma_f32_16x16x32_bf16 v[68:71], v[172:175], v[238:241], v[68:71]
	v_mfma_f32_16x16x32_bf16 v[96:99], v[168:171], v[214:217], v[96:99]
	v_mfma_f32_16x16x32_bf16 v[92:95], v[176:179], v[214:217], v[92:95]
	v_mfma_f32_16x16x32_bf16 v[88:91], v[168:171], v[222:225], v[88:91]
	v_mfma_f32_16x16x32_bf16 v[84:87], v[176:179], v[222:225], v[84:87]
	v_mfma_f32_16x16x32_bf16 v[80:83], v[168:171], v[234:237], v[80:83]
	v_mfma_f32_16x16x32_bf16 v[76:79], v[176:179], v[234:237], v[76:79]
	v_mfma_f32_16x16x32_bf16 v[72:75], v[168:171], v[242:245], v[72:75]
	v_mfma_f32_16x16x32_bf16 v[68:71], v[176:179], v[242:245], v[68:71]
	s_setprio 0
	s_setprio 1
	v_mfma_f32_16x16x32_bf16 v[64:67], v[180:183], v[210:213], v[64:67]
	v_mfma_f32_16x16x32_bf16 v[60:63], v[188:191], v[210:213], v[60:63]
	v_mfma_f32_16x16x32_bf16 v[56:59], v[180:183], v[218:221], v[56:59]
	v_mfma_f32_16x16x32_bf16 v[52:55], v[188:191], v[218:221], v[52:55]
	v_mfma_f32_16x16x32_bf16 v[48:51], v[180:183], v[230:233], v[48:51]
	v_mfma_f32_16x16x32_bf16 v[44:47], v[188:191], v[230:233], v[44:47]
	v_mfma_f32_16x16x32_bf16 v[40:43], v[180:183], v[238:241], v[40:43]
	v_mfma_f32_16x16x32_bf16 v[36:39], v[188:191], v[238:241], v[36:39]
	v_mfma_f32_16x16x32_bf16 v[64:67], v[184:187], v[214:217], v[64:67]
	v_mfma_f32_16x16x32_bf16 v[60:63], v[206:209], v[214:217], v[60:63]
	v_mfma_f32_16x16x32_bf16 v[56:59], v[184:187], v[222:225], v[56:59]
	v_mfma_f32_16x16x32_bf16 v[52:55], v[206:209], v[222:225], v[52:55]
	v_mfma_f32_16x16x32_bf16 v[48:51], v[184:187], v[234:237], v[48:51]
	v_mfma_f32_16x16x32_bf16 v[44:47], v[206:209], v[234:237], v[44:47]
	v_mfma_f32_16x16x32_bf16 v[40:43], v[184:187], v[242:245], v[40:43]
	v_mfma_f32_16x16x32_bf16 v[36:39], v[206:209], v[242:245], v[36:39]
	s_setprio 0
	s_barrier
	s_add_i32 s84, 0, 0x18000
	v_add_u32_e32 v1, s84, v204
	s_add_i32 s85, 0, 0x1c000
	ds_read_b128 v[164:167], v1
	ds_read_b128 v[168:171], v1 offset:1024
	ds_read_b128 v[172:175], v1 offset:2048
	ds_read_b128 v[176:179], v1 offset:3072
	v_add_u32_e32 v1, s85, v204
	ds_read_b128 v[180:183], v1
	ds_read_b128 v[184:187], v1 offset:1024
	ds_read_b128 v[188:191], v1 offset:2048
	ds_read_b128 v[206:209], v1 offset:3072
	s_add_u32 s56, s56, 0x40000
	s_addc_u32 s57, s57, 0
	s_mov_b32 m0, s62
	ds_read_b128 v[210:213], v205 offset:32768
	ds_read_b128 v[214:217], v205 offset:33792
	ds_read_b128 v[218:221], v205 offset:34816
	ds_read_b128 v[222:225], v205 offset:35840
	ds_read_b128 v[230:233], v205 offset:36864
	ds_read_b128 v[234:237], v205 offset:37888
	ds_read_b128 v[238:241], v205 offset:38912
	ds_read_b128 v[242:245], v205 offset:39936
	global_load_lds_dwordx4 v198, s[56:57]
	s_mov_b32 m0, s63
	s_nop 0
	global_load_lds_dwordx4 v194, s[56:57]
	s_waitcnt vmcnt(8)
	s_waitcnt lgkmcnt(0)
	s_barrier
	s_setprio 1
	s_waitcnt lgkmcnt(0)
	v_mfma_f32_16x16x32_bf16 v[160:163], v[164:167], v[210:213], v[160:163]
	v_mfma_f32_16x16x32_bf16 v[156:159], v[172:175], v[210:213], v[156:159]
	v_mfma_f32_16x16x32_bf16 v[152:155], v[164:167], v[218:221], v[152:155]
	v_mfma_f32_16x16x32_bf16 v[148:151], v[172:175], v[218:221], v[148:151]
	v_mfma_f32_16x16x32_bf16 v[144:147], v[164:167], v[230:233], v[144:147]
	v_mfma_f32_16x16x32_bf16 v[140:143], v[172:175], v[230:233], v[140:143]
	v_mfma_f32_16x16x32_bf16 v[136:139], v[164:167], v[238:241], v[136:139]
	v_mfma_f32_16x16x32_bf16 v[132:135], v[172:175], v[238:241], v[132:135]
	v_mfma_f32_16x16x32_bf16 v[160:163], v[168:171], v[214:217], v[160:163]
	v_mfma_f32_16x16x32_bf16 v[156:159], v[176:179], v[214:217], v[156:159]
	v_mfma_f32_16x16x32_bf16 v[152:155], v[168:171], v[222:225], v[152:155]
	v_mfma_f32_16x16x32_bf16 v[148:151], v[176:179], v[222:225], v[148:151]
	v_mfma_f32_16x16x32_bf16 v[144:147], v[168:171], v[234:237], v[144:147]
	v_mfma_f32_16x16x32_bf16 v[140:143], v[176:179], v[234:237], v[140:143]
	v_mfma_f32_16x16x32_bf16 v[136:139], v[168:171], v[242:245], v[136:139]
	v_mfma_f32_16x16x32_bf16 v[132:135], v[176:179], v[242:245], v[132:135]
	s_setprio 0
	s_setprio 1
	v_mfma_f32_16x16x32_bf16 v[128:131], v[180:183], v[210:213], v[128:131]
	v_mfma_f32_16x16x32_bf16 v[124:127], v[188:191], v[210:213], v[124:127]
	v_mfma_f32_16x16x32_bf16 v[120:123], v[180:183], v[218:221], v[120:123]
	v_mfma_f32_16x16x32_bf16 v[116:119], v[188:191], v[218:221], v[116:119]
	v_mfma_f32_16x16x32_bf16 v[112:115], v[180:183], v[230:233], v[112:115]
	v_mfma_f32_16x16x32_bf16 v[108:111], v[188:191], v[230:233], v[108:111]
	v_mfma_f32_16x16x32_bf16 v[104:107], v[180:183], v[238:241], v[104:107]
	v_mfma_f32_16x16x32_bf16 v[100:103], v[188:191], v[238:241], v[100:103]
	v_mfma_f32_16x16x32_bf16 v[128:131], v[184:187], v[214:217], v[128:131]
	v_mfma_f32_16x16x32_bf16 v[124:127], v[206:209], v[214:217], v[124:127]
	v_mfma_f32_16x16x32_bf16 v[120:123], v[184:187], v[222:225], v[120:123]
	v_mfma_f32_16x16x32_bf16 v[116:119], v[206:209], v[222:225], v[116:119]
	v_mfma_f32_16x16x32_bf16 v[112:115], v[184:187], v[234:237], v[112:115]
	v_mfma_f32_16x16x32_bf16 v[108:111], v[206:209], v[234:237], v[108:111]
	v_mfma_f32_16x16x32_bf16 v[104:107], v[184:187], v[242:245], v[104:107]
	v_mfma_f32_16x16x32_bf16 v[100:103], v[206:209], v[242:245], v[100:103]
	s_setprio 0
	s_barrier
	s_add_i32 s56, s84, s44
	v_lshl_add_u64 v[2:3], v[2:3], 0, s[16:17]
	s_mov_b32 m0, s56
	ds_read_b128 v[210:213], v205 offset:49152
	ds_read_b128 v[214:217], v205 offset:50176
	ds_read_b128 v[218:221], v205 offset:51200
	ds_read_b128 v[222:225], v205 offset:52224
	ds_read_b128 v[230:233], v205 offset:53248
	ds_read_b128 v[234:237], v205 offset:54272
	ds_read_b128 v[238:241], v205 offset:55296
	ds_read_b128 v[242:245], v205 offset:56320
	global_load_lds_dwordx4 v[2:3], off
	s_add_i32 m0, s56, 0x2000
	s_add_u32 s54, s54, 0x40080
	v_lshl_add_u64 v[2:3], v[226:227], 0, s[16:17]
	s_addc_u32 s55, s55, 0
	s_add_i32 s56, s85, s44
	global_load_lds_dwordx4 v[2:3], off
	s_mov_b32 m0, s56
	s_nop 0
	global_load_lds_dwordx4 v196, s[54:55]
	s_add_i32 m0, s56, 0x2000
	s_nop 0
	global_load_lds_dwordx4 v192, s[54:55]
	v_lshl_add_u64 v[2:3], v[246:247], 0, s[16:17]
	s_mov_b32 m0, s66
	s_nop 0
	global_load_lds_dwordx4 v[2:3], off
	v_lshl_add_u64 v[2:3], v[248:249], 0, s[16:17]
	s_mov_b32 m0, s67
	s_nop 0
	global_load_lds_dwordx4 v[2:3], off
	s_waitcnt vmcnt(8)
	s_waitcnt lgkmcnt(0)
	s_barrier
	s_setprio 1
	s_waitcnt lgkmcnt(0)
	v_mfma_f32_16x16x32_bf16 v[96:99], v[164:167], v[210:213], v[96:99]
	v_mfma_f32_16x16x32_bf16 v[92:95], v[172:175], v[210:213], v[92:95]
	v_mfma_f32_16x16x32_bf16 v[88:91], v[164:167], v[218:221], v[88:91]
	v_mfma_f32_16x16x32_bf16 v[84:87], v[172:175], v[218:221], v[84:87]
	v_mfma_f32_16x16x32_bf16 v[80:83], v[164:167], v[230:233], v[80:83]
	v_mfma_f32_16x16x32_bf16 v[76:79], v[172:175], v[230:233], v[76:79]
	v_mfma_f32_16x16x32_bf16 v[72:75], v[164:167], v[238:241], v[72:75]
	v_mfma_f32_16x16x32_bf16 v[68:71], v[172:175], v[238:241], v[68:71]
	v_mfma_f32_16x16x32_bf16 v[96:99], v[168:171], v[214:217], v[96:99]
	v_mfma_f32_16x16x32_bf16 v[92:95], v[176:179], v[214:217], v[92:95]
	v_mfma_f32_16x16x32_bf16 v[88:91], v[168:171], v[222:225], v[88:91]
	v_mfma_f32_16x16x32_bf16 v[84:87], v[176:179], v[222:225], v[84:87]
	v_mfma_f32_16x16x32_bf16 v[80:83], v[168:171], v[234:237], v[80:83]
	v_mfma_f32_16x16x32_bf16 v[76:79], v[176:179], v[234:237], v[76:79]
	v_mfma_f32_16x16x32_bf16 v[72:75], v[168:171], v[242:245], v[72:75]
	v_mfma_f32_16x16x32_bf16 v[68:71], v[176:179], v[242:245], v[68:71]
	s_setprio 0
	s_setprio 1
	v_mfma_f32_16x16x32_bf16 v[64:67], v[180:183], v[210:213], v[64:67]
	v_mfma_f32_16x16x32_bf16 v[60:63], v[188:191], v[210:213], v[60:63]
	v_mfma_f32_16x16x32_bf16 v[56:59], v[180:183], v[218:221], v[56:59]
	v_mfma_f32_16x16x32_bf16 v[52:55], v[188:191], v[218:221], v[52:55]
	v_mfma_f32_16x16x32_bf16 v[48:51], v[180:183], v[230:233], v[48:51]
	v_mfma_f32_16x16x32_bf16 v[44:47], v[188:191], v[230:233], v[44:47]
	v_mfma_f32_16x16x32_bf16 v[40:43], v[180:183], v[238:241], v[40:43]
	v_mfma_f32_16x16x32_bf16 v[36:39], v[188:191], v[238:241], v[36:39]
	v_mfma_f32_16x16x32_bf16 v[64:67], v[184:187], v[214:217], v[64:67]
	v_mfma_f32_16x16x32_bf16 v[60:63], v[206:209], v[214:217], v[60:63]
	v_mfma_f32_16x16x32_bf16 v[56:59], v[184:187], v[222:225], v[56:59]
	v_mfma_f32_16x16x32_bf16 v[52:55], v[206:209], v[222:225], v[52:55]
	v_mfma_f32_16x16x32_bf16 v[48:51], v[184:187], v[234:237], v[48:51]
	v_mfma_f32_16x16x32_bf16 v[44:47], v[206:209], v[234:237], v[44:47]
	v_mfma_f32_16x16x32_bf16 v[40:43], v[184:187], v[242:245], v[40:43]
	v_mfma_f32_16x16x32_bf16 v[36:39], v[206:209], v[242:245], v[36:39]
	s_setprio 0
	s_barrier
	s_add_i32 s83, s83, 2
	s_add_u32 s4, s4, 0x100
	s_addc_u32 s5, s5, 0
	s_add_u32 s81, s81, 0x100
	s_addc_u32 s82, s82, 0
	s_cmp_gt_u32 s83, 13
	s_cbranch_scc0 .LBB0_1034
	v_mbcnt_lo_u32_b32 v2, -1, 0
	v_mbcnt_hi_u32_b32 v2, -1, v2
	s_cmp_lg_u32 s78, 0
	v_and_b32_e32 v1, 15, v2
	s_cselect_b64 s[54:55], -1, 0
	s_cmp_eq_u32 s78, 0
	v_ashrrev_i32_e32 v2, 4, v2
	s_cbranch_scc1 .LBB0_1038
	v_cndmask_b32_e64 v3, 0, 1, s[54:55]
	v_cmp_ne_u32_e64 s[4:5], 1, v3
	s_andn2_b64 vcc, exec, s[54:55]
	s_cbranch_vccz .LBB0_1039

.LBB0_1142:
	ds_read_b128 v[128:131], v236
	ds_read_b128 v[132:135], v236 offset:1024
	ds_read_b128 v[136:139], v236 offset:2048
	ds_read_b128 v[140:143], v236 offset:3072
	ds_read_b128 v[144:147], v237
	ds_read_b128 v[148:151], v237 offset:1024
	ds_read_b128 v[152:155], v237 offset:2048
	ds_read_b128 v[156:159], v237 offset:3072
	s_add_u32 s36, s34, 0xfffc0080
	s_addc_u32 s37, s35, -1
	s_cmp_eq_u32 s71, 12
	s_cselect_b32 s39, s5, s37
	s_cselect_b32 s38, s9, s36
	s_cselect_b32 s37, s25, s70
	s_cselect_b32 s36, s27, s69
	s_add_i32 m0, s50, 0xc000
	ds_read_b128 v[160:163], v238
	ds_read_b128 v[164:167], v238 offset:1024
	ds_read_b128 v[168:171], v238 offset:2048
	ds_read_b128 v[172:175], v238 offset:3072
	ds_read_b128 v[176:179], v238 offset:4096
	ds_read_b128 v[180:183], v238 offset:5120
	ds_read_b128 v[198:201], v238 offset:6144
	ds_read_b128 v[202:205], v238 offset:7168
	global_load_lds_dwordx4 v194, s[34:35]
	s_add_i32 m0, s50, 0xe000
	s_nop 0
	global_load_lds_dwordx4 v196, s[34:35]
	s_waitcnt vmcnt(8)
	s_waitcnt lgkmcnt(0)
	s_barrier
	s_setprio 1
	s_waitcnt lgkmcnt(0)
	v_mfma_f32_16x16x32_bf16 v[124:127], v[128:131], v[160:163], v[124:127]
	v_mfma_f32_16x16x32_bf16 v[120:123], v[136:139], v[160:163], v[120:123]
	v_mfma_f32_16x16x32_bf16 v[108:111], v[128:131], v[168:171], v[108:111]
	v_mfma_f32_16x16x32_bf16 v[104:107], v[136:139], v[168:171], v[104:107]
	v_mfma_f32_16x16x32_bf16 v[92:95], v[128:131], v[176:179], v[92:95]
	v_mfma_f32_16x16x32_bf16 v[88:91], v[136:139], v[176:179], v[88:91]
	v_mfma_f32_16x16x32_bf16 v[76:79], v[128:131], v[198:201], v[76:79]
	v_mfma_f32_16x16x32_bf16 v[72:75], v[136:139], v[198:201], v[72:75]
	v_mfma_f32_16x16x32_bf16 v[124:127], v[132:135], v[164:167], v[124:127]
	v_mfma_f32_16x16x32_bf16 v[120:123], v[140:143], v[164:167], v[120:123]
	v_mfma_f32_16x16x32_bf16 v[108:111], v[132:135], v[172:175], v[108:111]
	v_mfma_f32_16x16x32_bf16 v[104:107], v[140:143], v[172:175], v[104:107]
	v_mfma_f32_16x16x32_bf16 v[92:95], v[132:135], v[180:183], v[92:95]
	v_mfma_f32_16x16x32_bf16 v[88:91], v[140:143], v[180:183], v[88:91]
	v_mfma_f32_16x16x32_bf16 v[76:79], v[132:135], v[202:205], v[76:79]
	v_mfma_f32_16x16x32_bf16 v[72:75], v[140:143], v[202:205], v[72:75]
	s_setprio 0
	s_setprio 1
	v_mfma_f32_16x16x32_bf16 v[116:119], v[144:147], v[160:163], v[116:119]
	v_mfma_f32_16x16x32_bf16 v[112:115], v[152:155], v[160:163], v[112:115]
	v_mfma_f32_16x16x32_bf16 v[100:103], v[144:147], v[168:171], v[100:103]
	v_mfma_f32_16x16x32_bf16 v[96:99], v[152:155], v[168:171], v[96:99]
	v_mfma_f32_16x16x32_bf16 v[84:87], v[144:147], v[176:179], v[84:87]
	v_mfma_f32_16x16x32_bf16 v[80:83], v[152:155], v[176:179], v[80:83]
	v_mfma_f32_16x16x32_bf16 v[68:71], v[144:147], v[198:201], v[68:71]
	v_mfma_f32_16x16x32_bf16 v[64:67], v[152:155], v[198:201], v[64:67]
	v_mfma_f32_16x16x32_bf16 v[116:119], v[148:151], v[164:167], v[116:119]
	v_mfma_f32_16x16x32_bf16 v[112:115], v[156:159], v[164:167], v[112:115]
	v_mfma_f32_16x16x32_bf16 v[100:103], v[148:151], v[172:175], v[100:103]
	v_mfma_f32_16x16x32_bf16 v[96:99], v[156:159], v[172:175], v[96:99]
	v_mfma_f32_16x16x32_bf16 v[84:87], v[148:151], v[180:183], v[84:87]
	v_mfma_f32_16x16x32_bf16 v[80:83], v[156:159], v[180:183], v[80:83]
	v_mfma_f32_16x16x32_bf16 v[68:71], v[148:151], v[202:205], v[68:71]
	v_mfma_f32_16x16x32_bf16 v[64:67], v[156:159], v[202:205], v[64:67]
	s_setprio 0
	s_barrier
	s_add_i32 s72, s65, s45
	v_lshl_add_u64 v[206:207], s[36:37], 0, v[186:187]
	s_mov_b32 m0, s72
	ds_read_b128 v[160:163], v238 offset:16384
	ds_read_b128 v[164:167], v238 offset:17408
	ds_read_b128 v[168:171], v238 offset:18432
	ds_read_b128 v[172:175], v238 offset:19456
	ds_read_b128 v[176:179], v238 offset:20480
	ds_read_b128 v[180:183], v238 offset:21504
	ds_read_b128 v[198:201], v238 offset:22528
	ds_read_b128 v[202:205], v238 offset:23552
	global_load_lds_dwordx4 v[206:207], off
	s_add_i32 m0, s72, 0x2000
	s_add_u32 s72, s36, 0x40000
	v_lshl_add_u64 v[208:209], s[36:37], 0, v[190:191]
	s_addc_u32 s73, s37, 0
	s_add_i32 s74, s66, s45
	global_load_lds_dwordx4 v[208:209], off
	s_mov_b32 m0, s74
	v_lshl_add_u64 v[212:213], s[38:39], 0, v[188:189]
	global_load_lds_dwordx4 v186, s[72:73]
	s_add_i32 m0, s74, 0x2000
	s_nop 0
	global_load_lds_dwordx4 v190, s[72:73]
	v_lshl_add_u64 v[210:211], s[38:39], 0, v[184:185]
	s_mov_b32 m0, s50
	s_nop 0
	global_load_lds_dwordx4 v[210:211], off
	s_mov_b32 m0, s51
	s_nop 0
	global_load_lds_dwordx4 v[212:213], off
	s_waitcnt vmcnt(8)
	s_waitcnt lgkmcnt(0)
	s_barrier
	s_setprio 1
	s_waitcnt lgkmcnt(0)
	v_mfma_f32_16x16x32_bf16 v[60:63], v[128:131], v[160:163], v[60:63]
	v_mfma_f32_16x16x32_bf16 v[56:59], v[136:139], v[160:163], v[56:59]
	v_mfma_f32_16x16x32_bf16 v[44:47], v[128:131], v[168:171], v[44:47]
	v_mfma_f32_16x16x32_bf16 v[40:43], v[136:139], v[168:171], v[40:43]
	v_mfma_f32_16x16x32_bf16 v[28:31], v[128:131], v[176:179], v[28:31]
	v_mfma_f32_16x16x32_bf16 v[24:27], v[136:139], v[176:179], v[24:27]
	v_mfma_f32_16x16x32_bf16 v[12:15], v[128:131], v[198:201], v[12:15]
	v_mfma_f32_16x16x32_bf16 v[8:11], v[136:139], v[198:201], v[8:11]
	v_mfma_f32_16x16x32_bf16 v[60:63], v[132:135], v[164:167], v[60:63]
	v_mfma_f32_16x16x32_bf16 v[56:59], v[140:143], v[164:167], v[56:59]
	v_mfma_f32_16x16x32_bf16 v[44:47], v[132:135], v[172:175], v[44:47]
	v_mfma_f32_16x16x32_bf16 v[40:43], v[140:143], v[172:175], v[40:43]
	v_mfma_f32_16x16x32_bf16 v[28:31], v[132:135], v[180:183], v[28:31]
	v_mfma_f32_16x16x32_bf16 v[24:27], v[140:143], v[180:183], v[24:27]
	v_mfma_f32_16x16x32_bf16 v[12:15], v[132:135], v[202:205], v[12:15]
	v_mfma_f32_16x16x32_bf16 v[8:11], v[140:143], v[202:205], v[8:11]
	s_setprio 0
	s_setprio 1
	v_mfma_f32_16x16x32_bf16 v[52:55], v[144:147], v[160:163], v[52:55]
	v_mfma_f32_16x16x32_bf16 v[48:51], v[152:155], v[160:163], v[48:51]
	v_mfma_f32_16x16x32_bf16 v[36:39], v[144:147], v[168:171], v[36:39]
	v_mfma_f32_16x16x32_bf16 v[32:35], v[152:155], v[168:171], v[32:35]
	v_mfma_f32_16x16x32_bf16 v[20:23], v[144:147], v[176:179], v[20:23]
	v_mfma_f32_16x16x32_bf16 v[16:19], v[152:155], v[176:179], v[16:19]
	v_mfma_f32_16x16x32_bf16 v[4:7], v[144:147], v[198:201], v[4:7]
	v_mfma_f32_16x16x32_bf16 v[0:3], v[152:155], v[198:201], v[0:3]
	v_mfma_f32_16x16x32_bf16 v[52:55], v[148:151], v[164:167], v[52:55]
	v_mfma_f32_16x16x32_bf16 v[48:51], v[156:159], v[164:167], v[48:51]
	v_mfma_f32_16x16x32_bf16 v[36:39], v[148:151], v[172:175], v[36:39]
	v_mfma_f32_16x16x32_bf16 v[32:35], v[156:159], v[172:175], v[32:35]
	v_mfma_f32_16x16x32_bf16 v[20:23], v[148:151], v[180:183], v[20:23]
	v_mfma_f32_16x16x32_bf16 v[16:19], v[156:159], v[180:183], v[16:19]
	v_mfma_f32_16x16x32_bf16 v[4:7], v[148:151], v[202:205], v[4:7]
	v_mfma_f32_16x16x32_bf16 v[0:3], v[156:159], v[202:205], v[0:3]
	s_setprio 0
	s_barrier
	s_add_i32 s72, 0, 0x18000
	s_add_i32 s73, 0, 0x1c000
	v_add_u32_e32 v140, s72, v231
	v_add_u32_e32 v156, s73, v231
	ds_read_b128 v[128:131], v140
	ds_read_b128 v[132:135], v140 offset:1024
	ds_read_b128 v[136:139], v140 offset:2048
	ds_read_b128 v[140:143], v140 offset:3072
	ds_read_b128 v[144:147], v156
	ds_read_b128 v[148:151], v156 offset:1024
	ds_read_b128 v[152:155], v156 offset:2048
	ds_read_b128 v[156:159], v156 offset:3072
	s_add_u32 s38, s38, 0x40000
	s_addc_u32 s39, s39, 0
	s_mov_b32 m0, s52
	ds_read_b128 v[160:163], v238 offset:32768
	ds_read_b128 v[164:167], v238 offset:33792
	ds_read_b128 v[168:171], v238 offset:34816
	ds_read_b128 v[172:175], v238 offset:35840
	ds_read_b128 v[176:179], v238 offset:36864
	ds_read_b128 v[180:183], v238 offset:37888
	ds_read_b128 v[198:201], v238 offset:38912
	ds_read_b128 v[202:205], v238 offset:39936
	global_load_lds_dwordx4 v184, s[38:39]
	s_mov_b32 m0, s53
	s_nop 0
	global_load_lds_dwordx4 v188, s[38:39]
	s_waitcnt vmcnt(8)
	s_waitcnt lgkmcnt(0)
	s_barrier
	s_setprio 1
	s_waitcnt lgkmcnt(0)
	v_mfma_f32_16x16x32_bf16 v[124:127], v[128:131], v[160:163], v[124:127]
	v_mfma_f32_16x16x32_bf16 v[120:123], v[136:139], v[160:163], v[120:123]
	v_mfma_f32_16x16x32_bf16 v[108:111], v[128:131], v[168:171], v[108:111]
	v_mfma_f32_16x16x32_bf16 v[104:107], v[136:139], v[168:171], v[104:107]
	v_mfma_f32_16x16x32_bf16 v[92:95], v[128:131], v[176:179], v[92:95]
	v_mfma_f32_16x16x32_bf16 v[88:91], v[136:139], v[176:179], v[88:91]
	v_mfma_f32_16x16x32_bf16 v[76:79], v[128:131], v[198:201], v[76:79]
	v_mfma_f32_16x16x32_bf16 v[72:75], v[136:139], v[198:201], v[72:75]
	v_mfma_f32_16x16x32_bf16 v[124:127], v[132:135], v[164:167], v[124:127]
	v_mfma_f32_16x16x32_bf16 v[120:123], v[140:143], v[164:167], v[120:123]
	v_mfma_f32_16x16x32_bf16 v[108:111], v[132:135], v[172:175], v[108:111]
	v_mfma_f32_16x16x32_bf16 v[104:107], v[140:143], v[172:175], v[104:107]
	v_mfma_f32_16x16x32_bf16 v[92:95], v[132:135], v[180:183], v[92:95]
	v_mfma_f32_16x16x32_bf16 v[88:91], v[140:143], v[180:183], v[88:91]
	v_mfma_f32_16x16x32_bf16 v[76:79], v[132:135], v[202:205], v[76:79]
	v_mfma_f32_16x16x32_bf16 v[72:75], v[140:143], v[202:205], v[72:75]
	s_setprio 0
	s_setprio 1
	v_mfma_f32_16x16x32_bf16 v[116:119], v[144:147], v[160:163], v[116:119]
	v_mfma_f32_16x16x32_bf16 v[112:115], v[152:155], v[160:163], v[112:115]
	v_mfma_f32_16x16x32_bf16 v[100:103], v[144:147], v[168:171], v[100:103]
	v_mfma_f32_16x16x32_bf16 v[96:99], v[152:155], v[168:171], v[96:99]
	v_mfma_f32_16x16x32_bf16 v[84:87], v[144:147], v[176:179], v[84:87]
	v_mfma_f32_16x16x32_bf16 v[80:83], v[152:155], v[176:179], v[80:83]
	v_mfma_f32_16x16x32_bf16 v[68:71], v[144:147], v[198:201], v[68:71]
	v_mfma_f32_16x16x32_bf16 v[64:67], v[152:155], v[198:201], v[64:67]
	v_mfma_f32_16x16x32_bf16 v[116:119], v[148:151], v[164:167], v[116:119]
	v_mfma_f32_16x16x32_bf16 v[112:115], v[156:159], v[164:167], v[112:115]
	v_mfma_f32_16x16x32_bf16 v[100:103], v[148:151], v[172:175], v[100:103]
	v_mfma_f32_16x16x32_bf16 v[96:99], v[156:159], v[172:175], v[96:99]
	v_mfma_f32_16x16x32_bf16 v[84:87], v[148:151], v[180:183], v[84:87]
	v_mfma_f32_16x16x32_bf16 v[80:83], v[156:159], v[180:183], v[80:83]
	v_mfma_f32_16x16x32_bf16 v[68:71], v[148:151], v[202:205], v[68:71]
	v_mfma_f32_16x16x32_bf16 v[64:67], v[156:159], v[202:205], v[64:67]
	s_setprio 0
	s_barrier
	s_add_i32 s38, s72, s45
	v_lshl_add_u64 v[206:207], v[206:207], 0, s[16:17]
	s_mov_b32 m0, s38
	ds_read_b128 v[160:163], v238 offset:49152
	ds_read_b128 v[164:167], v238 offset:50176
	ds_read_b128 v[168:171], v238 offset:51200
	ds_read_b128 v[172:175], v238 offset:52224
	ds_read_b128 v[176:179], v238 offset:53248
	ds_read_b128 v[180:183], v238 offset:54272
	ds_read_b128 v[198:201], v238 offset:55296
	ds_read_b128 v[202:205], v238 offset:56320
	global_load_lds_dwordx4 v[206:207], off
	s_add_i32 m0, s38, 0x2000
	s_add_u32 s36, s36, 0x40080
	v_lshl_add_u64 v[206:207], v[208:209], 0, s[16:17]
	s_addc_u32 s37, s37, 0
	s_add_i32 s38, s73, s45
	global_load_lds_dwordx4 v[206:207], off
	s_mov_b32 m0, s38
	s_nop 0
	global_load_lds_dwordx4 v186, s[36:37]
	s_add_i32 m0, s38, 0x2000
	s_nop 0
	global_load_lds_dwordx4 v190, s[36:37]
	v_lshl_add_u64 v[206:207], v[210:211], 0, s[16:17]
	s_mov_b32 m0, s56
	s_nop 0
	global_load_lds_dwordx4 v[206:207], off
	v_lshl_add_u64 v[206:207], v[212:213], 0, s[16:17]
	s_mov_b32 m0, s57
	s_nop 0
	global_load_lds_dwordx4 v[206:207], off
	s_waitcnt vmcnt(8)
	s_waitcnt lgkmcnt(0)
	s_barrier
	s_setprio 1
	s_waitcnt lgkmcnt(0)
	v_mfma_f32_16x16x32_bf16 v[60:63], v[128:131], v[160:163], v[60:63]
	v_mfma_f32_16x16x32_bf16 v[56:59], v[136:139], v[160:163], v[56:59]
	v_mfma_f32_16x16x32_bf16 v[44:47], v[128:131], v[168:171], v[44:47]
	v_mfma_f32_16x16x32_bf16 v[40:43], v[136:139], v[168:171], v[40:43]
	v_mfma_f32_16x16x32_bf16 v[28:31], v[128:131], v[176:179], v[28:31]
	v_mfma_f32_16x16x32_bf16 v[24:27], v[136:139], v[176:179], v[24:27]
	v_mfma_f32_16x16x32_bf16 v[12:15], v[128:131], v[198:201], v[12:15]
	v_mfma_f32_16x16x32_bf16 v[8:11], v[136:139], v[198:201], v[8:11]
	v_mfma_f32_16x16x32_bf16 v[60:63], v[132:135], v[164:167], v[60:63]
	v_mfma_f32_16x16x32_bf16 v[56:59], v[140:143], v[164:167], v[56:59]
	v_mfma_f32_16x16x32_bf16 v[44:47], v[132:135], v[172:175], v[44:47]
	v_mfma_f32_16x16x32_bf16 v[40:43], v[140:143], v[172:175], v[40:43]
	v_mfma_f32_16x16x32_bf16 v[28:31], v[132:135], v[180:183], v[28:31]
	v_mfma_f32_16x16x32_bf16 v[24:27], v[140:143], v[180:183], v[24:27]
	v_mfma_f32_16x16x32_bf16 v[12:15], v[132:135], v[202:205], v[12:15]
	v_mfma_f32_16x16x32_bf16 v[8:11], v[140:143], v[202:205], v[8:11]
	s_setprio 0
	s_setprio 1
	v_mfma_f32_16x16x32_bf16 v[52:55], v[144:147], v[160:163], v[52:55]
	v_mfma_f32_16x16x32_bf16 v[48:51], v[152:155], v[160:163], v[48:51]
	v_mfma_f32_16x16x32_bf16 v[36:39], v[144:147], v[168:171], v[36:39]
	v_mfma_f32_16x16x32_bf16 v[32:35], v[152:155], v[168:171], v[32:35]
	v_mfma_f32_16x16x32_bf16 v[20:23], v[144:147], v[176:179], v[20:23]
	v_mfma_f32_16x16x32_bf16 v[16:19], v[152:155], v[176:179], v[16:19]
	v_mfma_f32_16x16x32_bf16 v[4:7], v[144:147], v[198:201], v[4:7]
	v_mfma_f32_16x16x32_bf16 v[0:3], v[152:155], v[198:201], v[0:3]
	v_mfma_f32_16x16x32_bf16 v[52:55], v[148:151], v[164:167], v[52:55]
	v_mfma_f32_16x16x32_bf16 v[48:51], v[156:159], v[164:167], v[48:51]
	v_mfma_f32_16x16x32_bf16 v[36:39], v[148:151], v[172:175], v[36:39]
	v_mfma_f32_16x16x32_bf16 v[32:35], v[156:159], v[172:175], v[32:35]
	v_mfma_f32_16x16x32_bf16 v[20:23], v[148:151], v[180:183], v[20:23]
	v_mfma_f32_16x16x32_bf16 v[16:19], v[156:159], v[180:183], v[16:19]
	v_mfma_f32_16x16x32_bf16 v[4:7], v[148:151], v[202:205], v[4:7]
	v_mfma_f32_16x16x32_bf16 v[0:3], v[156:159], v[202:205], v[0:3]
	s_setprio 0
	s_barrier
	s_add_i32 s71, s71, 2
	s_add_u32 s34, s34, 0x100
	s_addc_u32 s35, s35, 0
	s_add_u32 s69, s69, 0x100
	s_addc_u32 s70, s70, 0
	s_cmp_gt_u32 s71, 13
	s_cbranch_scc0 .LBB0_1142
	s_and_b64 vcc, exec, s[20:21]
	s_cbranch_vccz .LBB0_1145
	s_barrier

.Lg5_peel:
	ds_read_b128 v[138:141], v193
	ds_read_b128 v[142:145], v193 offset:1024
	ds_read_b128 v[146:149], v193 offset:2048
	ds_read_b128 v[150:153], v193 offset:3072
	ds_read_b128 v[154:157], v195
	ds_read_b128 v[158:161], v195 offset:1024
	ds_read_b128 v[162:165], v195 offset:2048
	ds_read_b128 v[182:185], v195 offset:3072
	s_add_u32 s58, s56, 0xfffc0080
	s_addc_u32 s59, s57, -1
	s_cmp_eq_u32 s86, 12
	s_cselect_b32 s61, s5, s59
	s_cselect_b32 s60, s37, s58
	s_cselect_b32 s59, s39, s85
	s_cselect_b32 s58, s55, s84
	s_add_i32 m0, s46, 0xc000
	ds_read_b128 v[198:201], v197
	ds_read_b128 v[202:205], v197 offset:1024
	ds_read_b128 v[210:213], v197 offset:2048
	ds_read_b128 v[214:217], v197 offset:3072
	ds_read_b128 v[218:221], v197 offset:4096
	ds_read_b128 v[222:225], v197 offset:5120
	ds_read_b128 v[230:233], v197 offset:6144
	ds_read_b128 v[234:237], v197 offset:7168
	global_load_lds_dwordx4 v178, s[56:57]
	s_add_i32 m0, s46, 0xe000
	s_nop 0
	global_load_lds_dwordx4 v180, s[56:57]
	s_waitcnt lgkmcnt(0)
	s_barrier
	s_setprio 1
	s_waitcnt lgkmcnt(0)
	v_mfma_f32_16x16x32_bf16 v[32:35], v[138:141], v[198:201], 0
	v_mfma_f32_16x16x32_bf16 v[28:31], v[146:149], v[198:201], 0
	v_mfma_f32_16x16x32_bf16 v[132:135], v[138:141], v[210:213], 0
	v_mfma_f32_16x16x32_bf16 v[128:131], v[146:149], v[210:213], 0
	v_mfma_f32_16x16x32_bf16 v[124:127], v[138:141], v[218:221], 0
	v_mfma_f32_16x16x32_bf16 v[120:123], v[146:149], v[218:221], 0
	v_mfma_f32_16x16x32_bf16 v[40:43], v[138:141], v[230:233], 0
	v_mfma_f32_16x16x32_bf16 v[36:39], v[146:149], v[230:233], 0
	v_mfma_f32_16x16x32_bf16 v[32:35], v[142:145], v[202:205], v[32:35]
	v_mfma_f32_16x16x32_bf16 v[28:31], v[150:153], v[202:205], v[28:31]
	v_mfma_f32_16x16x32_bf16 v[132:135], v[142:145], v[214:217], v[132:135]
	v_mfma_f32_16x16x32_bf16 v[128:131], v[150:153], v[214:217], v[128:131]
	v_mfma_f32_16x16x32_bf16 v[124:127], v[142:145], v[222:225], v[124:127]
	v_mfma_f32_16x16x32_bf16 v[120:123], v[150:153], v[222:225], v[120:123]
	v_mfma_f32_16x16x32_bf16 v[40:43], v[142:145], v[234:237], v[40:43]
	v_mfma_f32_16x16x32_bf16 v[36:39], v[150:153], v[234:237], v[36:39]
	s_setprio 0
	s_setprio 1
	v_mfma_f32_16x16x32_bf16 v[16:19], v[154:157], v[198:201], 0
	v_mfma_f32_16x16x32_bf16 v[12:15], v[162:165], v[198:201], 0
	v_mfma_f32_16x16x32_bf16 v[116:119], v[154:157], v[210:213], 0
	v_mfma_f32_16x16x32_bf16 v[112:115], v[162:165], v[210:213], 0
	v_mfma_f32_16x16x32_bf16 v[108:111], v[154:157], v[218:221], 0
	v_mfma_f32_16x16x32_bf16 v[104:107], v[162:165], v[218:221], 0
	v_mfma_f32_16x16x32_bf16 v[100:103], v[154:157], v[230:233], 0
	v_mfma_f32_16x16x32_bf16 v[96:99], v[162:165], v[230:233], 0
	v_mfma_f32_16x16x32_bf16 v[16:19], v[158:161], v[202:205], v[16:19]
	v_mfma_f32_16x16x32_bf16 v[12:15], v[182:185], v[202:205], v[12:15]
	v_mfma_f32_16x16x32_bf16 v[116:119], v[158:161], v[214:217], v[116:119]
	v_mfma_f32_16x16x32_bf16 v[112:115], v[182:185], v[214:217], v[112:115]
	v_mfma_f32_16x16x32_bf16 v[108:111], v[158:161], v[222:225], v[108:111]
	v_mfma_f32_16x16x32_bf16 v[104:107], v[182:185], v[222:225], v[104:107]
	v_mfma_f32_16x16x32_bf16 v[100:103], v[158:161], v[234:237], v[100:103]
	v_mfma_f32_16x16x32_bf16 v[96:99], v[182:185], v[234:237], v[96:99]
	s_setprio 0
	s_barrier
	s_add_i32 s87, s78, s35
	v_lshl_add_u64 v[166:167], s[58:59], 0, v[172:173]
	s_mov_b32 m0, s87
	ds_read_b128 v[198:201], v197 offset:16384
	ds_read_b128 v[202:205], v197 offset:17408
	ds_read_b128 v[210:213], v197 offset:18432
	ds_read_b128 v[214:217], v197 offset:19456
	ds_read_b128 v[218:221], v197 offset:20480
	ds_read_b128 v[222:225], v197 offset:21504
	ds_read_b128 v[230:233], v197 offset:22528
	ds_read_b128 v[234:237], v197 offset:23552
	global_load_lds_dwordx4 v[166:167], off
	s_add_i32 m0, s87, 0x2000
	s_add_u32 s90, s58, 0x40000
	v_lshl_add_u64 v[188:189], s[58:59], 0, v[168:169]
	s_addc_u32 s91, s59, 0
	s_add_i32 s87, s79, s35
	global_load_lds_dwordx4 v[188:189], off
	s_mov_b32 m0, s87
	v_lshl_add_u64 v[228:229], s[60:61], 0, v[170:171]
	global_load_lds_dwordx4 v172, s[90:91]
	s_add_i32 m0, s87, 0x2000
	s_nop 0
	global_load_lds_dwordx4 v168, s[90:91]
	v_lshl_add_u64 v[226:227], s[60:61], 0, v[174:175]
	s_mov_b32 m0, s46
	s_nop 0
	global_load_lds_dwordx4 v[226:227], off
	s_mov_b32 m0, s47
	s_nop 0
	global_load_lds_dwordx4 v[228:229], off
	s_waitcnt lgkmcnt(0)
	s_barrier
	s_setprio 1
	s_waitcnt lgkmcnt(0)
	v_mfma_f32_16x16x32_bf16 v[92:95], v[138:141], v[198:201], 0
	v_mfma_f32_16x16x32_bf16 v[88:91], v[146:149], v[198:201], 0
	v_mfma_f32_16x16x32_bf16 v[84:87], v[138:141], v[210:213], 0
	v_mfma_f32_16x16x32_bf16 v[80:83], v[146:149], v[210:213], 0
	v_mfma_f32_16x16x32_bf16 v[68:71], v[138:141], v[218:221], 0
	v_mfma_f32_16x16x32_bf16 v[64:67], v[146:149], v[218:221], 0
	v_mfma_f32_16x16x32_bf16 v[24:27], v[138:141], v[230:233], 0
	v_mfma_f32_16x16x32_bf16 v[20:23], v[146:149], v[230:233], 0
	v_mfma_f32_16x16x32_bf16 v[92:95], v[142:145], v[202:205], v[92:95]
	v_mfma_f32_16x16x32_bf16 v[88:91], v[150:153], v[202:205], v[88:91]
	v_mfma_f32_16x16x32_bf16 v[84:87], v[142:145], v[214:217], v[84:87]
	v_mfma_f32_16x16x32_bf16 v[80:83], v[150:153], v[214:217], v[80:83]
	v_mfma_f32_16x16x32_bf16 v[68:71], v[142:145], v[222:225], v[68:71]
	v_mfma_f32_16x16x32_bf16 v[64:67], v[150:153], v[222:225], v[64:67]
	v_mfma_f32_16x16x32_bf16 v[24:27], v[142:145], v[234:237], v[24:27]
	v_mfma_f32_16x16x32_bf16 v[20:23], v[150:153], v[234:237], v[20:23]
	s_setprio 0
	s_setprio 1
	v_mfma_f32_16x16x32_bf16 v[76:79], v[154:157], v[198:201], 0
	v_mfma_f32_16x16x32_bf16 v[72:75], v[162:165], v[198:201], 0
	v_mfma_f32_16x16x32_bf16 v[60:63], v[154:157], v[210:213], 0
	v_mfma_f32_16x16x32_bf16 v[56:59], v[162:165], v[210:213], 0
	v_mfma_f32_16x16x32_bf16 v[52:55], v[154:157], v[218:221], 0
	v_mfma_f32_16x16x32_bf16 v[48:51], v[162:165], v[218:221], 0
	v_mfma_f32_16x16x32_bf16 v[44:47], v[154:157], v[230:233], 0
	v_mfma_f32_16x16x32_bf16 v[0:3], v[162:165], v[230:233], 0
	v_mfma_f32_16x16x32_bf16 v[76:79], v[158:161], v[202:205], v[76:79]
	v_mfma_f32_16x16x32_bf16 v[72:75], v[182:185], v[202:205], v[72:75]
	v_mfma_f32_16x16x32_bf16 v[60:63], v[158:161], v[214:217], v[60:63]
	v_mfma_f32_16x16x32_bf16 v[56:59], v[182:185], v[214:217], v[56:59]
	v_mfma_f32_16x16x32_bf16 v[52:55], v[158:161], v[222:225], v[52:55]
	v_mfma_f32_16x16x32_bf16 v[48:51], v[182:185], v[222:225], v[48:51]
	v_mfma_f32_16x16x32_bf16 v[44:47], v[158:161], v[234:237], v[44:47]
	v_mfma_f32_16x16x32_bf16 v[0:3], v[182:185], v[234:237], v[0:3]
	s_setprio 0
	s_barrier
	s_branch .Lg5_mid
.LBB0_1258:
	ds_read_b128 v[138:141], v193
	ds_read_b128 v[142:145], v193 offset:1024
	ds_read_b128 v[146:149], v193 offset:2048
	ds_read_b128 v[150:153], v193 offset:3072
	ds_read_b128 v[154:157], v195
	ds_read_b128 v[158:161], v195 offset:1024
	ds_read_b128 v[162:165], v195 offset:2048
	ds_read_b128 v[182:185], v195 offset:3072
	s_add_u32 s58, s56, 0xfffc0080
	s_addc_u32 s59, s57, -1
	s_cmp_eq_u32 s86, 12
	s_cselect_b32 s61, s5, s59
	s_cselect_b32 s60, s37, s58
	s_cselect_b32 s59, s39, s85
	s_cselect_b32 s58, s55, s84
	s_add_i32 m0, s46, 0xc000
	ds_read_b128 v[198:201], v197
	ds_read_b128 v[202:205], v197 offset:1024
	ds_read_b128 v[210:213], v197 offset:2048
	ds_read_b128 v[214:217], v197 offset:3072
	ds_read_b128 v[218:221], v197 offset:4096
	ds_read_b128 v[222:225], v197 offset:5120
	ds_read_b128 v[230:233], v197 offset:6144
	ds_read_b128 v[234:237], v197 offset:7168
	global_load_lds_dwordx4 v178, s[56:57]
	s_add_i32 m0, s46, 0xe000
	s_nop 0
	global_load_lds_dwordx4 v180, s[56:57]
	s_waitcnt vmcnt(8)
	s_waitcnt lgkmcnt(0)
	s_barrier
	s_setprio 1
	s_waitcnt lgkmcnt(0)
	v_mfma_f32_16x16x32_bf16 v[32:35], v[138:141], v[198:201], v[32:35]
	v_mfma_f32_16x16x32_bf16 v[28:31], v[146:149], v[198:201], v[28:31]
	v_mfma_f32_16x16x32_bf16 v[132:135], v[138:141], v[210:213], v[132:135]
	v_mfma_f32_16x16x32_bf16 v[128:131], v[146:149], v[210:213], v[128:131]
	v_mfma_f32_16x16x32_bf16 v[124:127], v[138:141], v[218:221], v[124:127]
	v_mfma_f32_16x16x32_bf16 v[120:123], v[146:149], v[218:221], v[120:123]
	v_mfma_f32_16x16x32_bf16 v[40:43], v[138:141], v[230:233], v[40:43]
	v_mfma_f32_16x16x32_bf16 v[36:39], v[146:149], v[230:233], v[36:39]
	v_mfma_f32_16x16x32_bf16 v[32:35], v[142:145], v[202:205], v[32:35]
	v_mfma_f32_16x16x32_bf16 v[28:31], v[150:153], v[202:205], v[28:31]
	v_mfma_f32_16x16x32_bf16 v[132:135], v[142:145], v[214:217], v[132:135]
	v_mfma_f32_16x16x32_bf16 v[128:131], v[150:153], v[214:217], v[128:131]
	v_mfma_f32_16x16x32_bf16 v[124:127], v[142:145], v[222:225], v[124:127]
	v_mfma_f32_16x16x32_bf16 v[120:123], v[150:153], v[222:225], v[120:123]
	v_mfma_f32_16x16x32_bf16 v[40:43], v[142:145], v[234:237], v[40:43]
	v_mfma_f32_16x16x32_bf16 v[36:39], v[150:153], v[234:237], v[36:39]
	s_setprio 0
	s_setprio 1
	v_mfma_f32_16x16x32_bf16 v[16:19], v[154:157], v[198:201], v[16:19]
	v_mfma_f32_16x16x32_bf16 v[12:15], v[162:165], v[198:201], v[12:15]
	v_mfma_f32_16x16x32_bf16 v[116:119], v[154:157], v[210:213], v[116:119]
	v_mfma_f32_16x16x32_bf16 v[112:115], v[162:165], v[210:213], v[112:115]
	v_mfma_f32_16x16x32_bf16 v[108:111], v[154:157], v[218:221], v[108:111]
	v_mfma_f32_16x16x32_bf16 v[104:107], v[162:165], v[218:221], v[104:107]
	v_mfma_f32_16x16x32_bf16 v[100:103], v[154:157], v[230:233], v[100:103]
	v_mfma_f32_16x16x32_bf16 v[96:99], v[162:165], v[230:233], v[96:99]
	v_mfma_f32_16x16x32_bf16 v[16:19], v[158:161], v[202:205], v[16:19]
	v_mfma_f32_16x16x32_bf16 v[12:15], v[182:185], v[202:205], v[12:15]
	v_mfma_f32_16x16x32_bf16 v[116:119], v[158:161], v[214:217], v[116:119]
	v_mfma_f32_16x16x32_bf16 v[112:115], v[182:185], v[214:217], v[112:115]
	v_mfma_f32_16x16x32_bf16 v[108:111], v[158:161], v[222:225], v[108:111]
	v_mfma_f32_16x16x32_bf16 v[104:107], v[182:185], v[222:225], v[104:107]
	v_mfma_f32_16x16x32_bf16 v[100:103], v[158:161], v[234:237], v[100:103]
	v_mfma_f32_16x16x32_bf16 v[96:99], v[182:185], v[234:237], v[96:99]
	s_setprio 0
	s_barrier
	s_add_i32 s87, s78, s35
	v_lshl_add_u64 v[166:167], s[58:59], 0, v[172:173]
	s_mov_b32 m0, s87
	ds_read_b128 v[198:201], v197 offset:16384
	ds_read_b128 v[202:205], v197 offset:17408
	ds_read_b128 v[210:213], v197 offset:18432
	ds_read_b128 v[214:217], v197 offset:19456
	ds_read_b128 v[218:221], v197 offset:20480
	ds_read_b128 v[222:225], v197 offset:21504
	ds_read_b128 v[230:233], v197 offset:22528
	ds_read_b128 v[234:237], v197 offset:23552
	global_load_lds_dwordx4 v[166:167], off
	s_add_i32 m0, s87, 0x2000
	s_add_u32 s90, s58, 0x40000
	v_lshl_add_u64 v[188:189], s[58:59], 0, v[168:169]
	s_addc_u32 s91, s59, 0
	s_add_i32 s87, s79, s35
	global_load_lds_dwordx4 v[188:189], off
	s_mov_b32 m0, s87
	v_lshl_add_u64 v[228:229], s[60:61], 0, v[170:171]
	global_load_lds_dwordx4 v172, s[90:91]
	s_add_i32 m0, s87, 0x2000
	s_nop 0
	global_load_lds_dwordx4 v168, s[90:91]
	v_lshl_add_u64 v[226:227], s[60:61], 0, v[174:175]
	s_mov_b32 m0, s46
	s_nop 0
	global_load_lds_dwordx4 v[226:227], off
	s_mov_b32 m0, s47
	s_nop 0
	global_load_lds_dwordx4 v[228:229], off
	s_waitcnt vmcnt(8)
	s_waitcnt lgkmcnt(0)
	s_barrier
	s_setprio 1
	s_waitcnt lgkmcnt(0)
	v_mfma_f32_16x16x32_bf16 v[92:95], v[138:141], v[198:201], v[92:95]
	v_mfma_f32_16x16x32_bf16 v[88:91], v[146:149], v[198:201], v[88:91]
	v_mfma_f32_16x16x32_bf16 v[84:87], v[138:141], v[210:213], v[84:87]
	v_mfma_f32_16x16x32_bf16 v[80:83], v[146:149], v[210:213], v[80:83]
	v_mfma_f32_16x16x32_bf16 v[68:71], v[138:141], v[218:221], v[68:71]
	v_mfma_f32_16x16x32_bf16 v[64:67], v[146:149], v[218:221], v[64:67]
	v_mfma_f32_16x16x32_bf16 v[24:27], v[138:141], v[230:233], v[24:27]
	v_mfma_f32_16x16x32_bf16 v[20:23], v[146:149], v[230:233], v[20:23]
	v_mfma_f32_16x16x32_bf16 v[92:95], v[142:145], v[202:205], v[92:95]
	v_mfma_f32_16x16x32_bf16 v[88:91], v[150:153], v[202:205], v[88:91]
	v_mfma_f32_16x16x32_bf16 v[84:87], v[142:145], v[214:217], v[84:87]
	v_mfma_f32_16x16x32_bf16 v[80:83], v[150:153], v[214:217], v[80:83]
	v_mfma_f32_16x16x32_bf16 v[68:71], v[142:145], v[222:225], v[68:71]
	v_mfma_f32_16x16x32_bf16 v[64:67], v[150:153], v[222:225], v[64:67]
	v_mfma_f32_16x16x32_bf16 v[24:27], v[142:145], v[234:237], v[24:27]
	v_mfma_f32_16x16x32_bf16 v[20:23], v[150:153], v[234:237], v[20:23]
	s_setprio 0
	s_setprio 1
	v_mfma_f32_16x16x32_bf16 v[76:79], v[154:157], v[198:201], v[76:79]
	v_mfma_f32_16x16x32_bf16 v[72:75], v[162:165], v[198:201], v[72:75]
	v_mfma_f32_16x16x32_bf16 v[60:63], v[154:157], v[210:213], v[60:63]
	v_mfma_f32_16x16x32_bf16 v[56:59], v[162:165], v[210:213], v[56:59]
	v_mfma_f32_16x16x32_bf16 v[52:55], v[154:157], v[218:221], v[52:55]
	v_mfma_f32_16x16x32_bf16 v[48:51], v[162:165], v[218:221], v[48:51]
	v_mfma_f32_16x16x32_bf16 v[44:47], v[154:157], v[230:233], v[44:47]
	v_mfma_f32_16x16x32_bf16 v[0:3], v[162:165], v[230:233], v[0:3]
	v_mfma_f32_16x16x32_bf16 v[76:79], v[158:161], v[202:205], v[76:79]
	v_mfma_f32_16x16x32_bf16 v[72:75], v[182:185], v[202:205], v[72:75]
	v_mfma_f32_16x16x32_bf16 v[60:63], v[158:161], v[214:217], v[60:63]
	v_mfma_f32_16x16x32_bf16 v[56:59], v[182:185], v[214:217], v[56:59]
	v_mfma_f32_16x16x32_bf16 v[52:55], v[158:161], v[222:225], v[52:55]
	v_mfma_f32_16x16x32_bf16 v[48:51], v[182:185], v[222:225], v[48:51]
	v_mfma_f32_16x16x32_bf16 v[44:47], v[158:161], v[234:237], v[44:47]
	v_mfma_f32_16x16x32_bf16 v[0:3], v[182:185], v[234:237], v[0:3]
	s_setprio 0
	s_barrier
.Lg5_mid:
	s_add_i32 s87, 0, 0x18000
	v_add_u32_e32 v137, s87, v187
	s_add_i32 s90, 0, 0x1c000
	ds_read_b128 v[138:141], v137
	ds_read_b128 v[142:145], v137 offset:1024
	ds_read_b128 v[146:149], v137 offset:2048
	ds_read_b128 v[150:153], v137 offset:3072
	v_add_u32_e32 v137, s90, v187
	ds_read_b128 v[154:157], v137
	ds_read_b128 v[158:161], v137 offset:1024
	ds_read_b128 v[162:165], v137 offset:2048
	ds_read_b128 v[182:185], v137 offset:3072
	s_add_u32 s60, s60, 0x40000
	s_addc_u32 s61, s61, 0
	s_mov_b32 m0, s62
	ds_read_b128 v[198:201], v197 offset:32768
	ds_read_b128 v[202:205], v197 offset:33792
	ds_read_b128 v[210:213], v197 offset:34816
	ds_read_b128 v[214:217], v197 offset:35840
	ds_read_b128 v[218:221], v197 offset:36864
	ds_read_b128 v[222:225], v197 offset:37888
	ds_read_b128 v[230:233], v197 offset:38912
	ds_read_b128 v[234:237], v197 offset:39936
	global_load_lds_dwordx4 v174, s[60:61]
	s_mov_b32 m0, s63
	s_nop 0
	global_load_lds_dwordx4 v170, s[60:61]
	s_waitcnt vmcnt(8)
	s_waitcnt lgkmcnt(0)
	s_barrier
	s_setprio 1
	s_waitcnt lgkmcnt(0)
	v_mfma_f32_16x16x32_bf16 v[32:35], v[138:141], v[198:201], v[32:35]
	v_mfma_f32_16x16x32_bf16 v[28:31], v[146:149], v[198:201], v[28:31]
	v_mfma_f32_16x16x32_bf16 v[132:135], v[138:141], v[210:213], v[132:135]
	v_mfma_f32_16x16x32_bf16 v[128:131], v[146:149], v[210:213], v[128:131]
	v_mfma_f32_16x16x32_bf16 v[124:127], v[138:141], v[218:221], v[124:127]
	v_mfma_f32_16x16x32_bf16 v[120:123], v[146:149], v[218:221], v[120:123]
	v_mfma_f32_16x16x32_bf16 v[40:43], v[138:141], v[230:233], v[40:43]
	v_mfma_f32_16x16x32_bf16 v[36:39], v[146:149], v[230:233], v[36:39]
	v_mfma_f32_16x16x32_bf16 v[32:35], v[142:145], v[202:205], v[32:35]
	v_mfma_f32_16x16x32_bf16 v[28:31], v[150:153], v[202:205], v[28:31]
	v_mfma_f32_16x16x32_bf16 v[132:135], v[142:145], v[214:217], v[132:135]
	v_mfma_f32_16x16x32_bf16 v[128:131], v[150:153], v[214:217], v[128:131]
	v_mfma_f32_16x16x32_bf16 v[124:127], v[142:145], v[222:225], v[124:127]
	v_mfma_f32_16x16x32_bf16 v[120:123], v[150:153], v[222:225], v[120:123]
	v_mfma_f32_16x16x32_bf16 v[40:43], v[142:145], v[234:237], v[40:43]
	v_mfma_f32_16x16x32_bf16 v[36:39], v[150:153], v[234:237], v[36:39]
	s_setprio 0
	s_setprio 1
	v_mfma_f32_16x16x32_bf16 v[16:19], v[154:157], v[198:201], v[16:19]
	v_mfma_f32_16x16x32_bf16 v[12:15], v[162:165], v[198:201], v[12:15]
	v_mfma_f32_16x16x32_bf16 v[116:119], v[154:157], v[210:213], v[116:119]
	v_mfma_f32_16x16x32_bf16 v[112:115], v[162:165], v[210:213], v[112:115]
	v_mfma_f32_16x16x32_bf16 v[108:111], v[154:157], v[218:221], v[108:111]
	v_mfma_f32_16x16x32_bf16 v[104:107], v[162:165], v[218:221], v[104:107]
	v_mfma_f32_16x16x32_bf16 v[100:103], v[154:157], v[230:233], v[100:103]
	v_mfma_f32_16x16x32_bf16 v[96:99], v[162:165], v[230:233], v[96:99]
	v_mfma_f32_16x16x32_bf16 v[16:19], v[158:161], v[202:205], v[16:19]
	v_mfma_f32_16x16x32_bf16 v[12:15], v[182:185], v[202:205], v[12:15]
	v_mfma_f32_16x16x32_bf16 v[116:119], v[158:161], v[214:217], v[116:119]
	v_mfma_f32_16x16x32_bf16 v[112:115], v[182:185], v[214:217], v[112:115]
	v_mfma_f32_16x16x32_bf16 v[108:111], v[158:161], v[222:225], v[108:111]
	v_mfma_f32_16x16x32_bf16 v[104:107], v[182:185], v[222:225], v[104:107]
	v_mfma_f32_16x16x32_bf16 v[100:103], v[158:161], v[234:237], v[100:103]
	v_mfma_f32_16x16x32_bf16 v[96:99], v[182:185], v[234:237], v[96:99]
	s_setprio 0
	s_barrier
	s_add_i32 s60, s87, s35
	v_lshl_add_u64 v[166:167], v[166:167], 0, s[14:15]
	s_mov_b32 m0, s60
	ds_read_b128 v[198:201], v197 offset:49152
	ds_read_b128 v[202:205], v197 offset:50176
	ds_read_b128 v[210:213], v197 offset:51200
	ds_read_b128 v[214:217], v197 offset:52224
	ds_read_b128 v[218:221], v197 offset:53248
	ds_read_b128 v[222:225], v197 offset:54272
	ds_read_b128 v[230:233], v197 offset:55296
	ds_read_b128 v[234:237], v197 offset:56320
	global_load_lds_dwordx4 v[166:167], off
	s_add_i32 m0, s60, 0x2000
	s_add_u32 s58, s58, 0x40080
	v_lshl_add_u64 v[166:167], v[188:189], 0, s[14:15]
	s_addc_u32 s59, s59, 0
	s_add_i32 s60, s90, s35
	global_load_lds_dwordx4 v[166:167], off
	s_mov_b32 m0, s60
	s_nop 0
	global_load_lds_dwordx4 v172, s[58:59]
	s_add_i32 m0, s60, 0x2000
	s_nop 0
	global_load_lds_dwordx4 v168, s[58:59]
	v_lshl_add_u64 v[166:167], v[226:227], 0, s[14:15]
	s_mov_b32 m0, s67
	s_nop 0
	global_load_lds_dwordx4 v[166:167], off
	v_lshl_add_u64 v[166:167], v[228:229], 0, s[14:15]
	s_mov_b32 m0, s68
	s_nop 0
	global_load_lds_dwordx4 v[166:167], off
	s_waitcnt vmcnt(8)
	s_waitcnt lgkmcnt(0)
	s_barrier
	s_setprio 1
	s_waitcnt lgkmcnt(0)
	v_mfma_f32_16x16x32_bf16 v[92:95], v[138:141], v[198:201], v[92:95]
	v_mfma_f32_16x16x32_bf16 v[88:91], v[146:149], v[198:201], v[88:91]
	v_mfma_f32_16x16x32_bf16 v[84:87], v[138:141], v[210:213], v[84:87]
	v_mfma_f32_16x16x32_bf16 v[80:83], v[146:149], v[210:213], v[80:83]
	v_mfma_f32_16x16x32_bf16 v[68:71], v[138:141], v[218:221], v[68:71]
	v_mfma_f32_16x16x32_bf16 v[64:67], v[146:149], v[218:221], v[64:67]
	v_mfma_f32_16x16x32_bf16 v[24:27], v[138:141], v[230:233], v[24:27]
	v_mfma_f32_16x16x32_bf16 v[20:23], v[146:149], v[230:233], v[20:23]
	v_mfma_f32_16x16x32_bf16 v[92:95], v[142:145], v[202:205], v[92:95]
	v_mfma_f32_16x16x32_bf16 v[88:91], v[150:153], v[202:205], v[88:91]
	v_mfma_f32_16x16x32_bf16 v[84:87], v[142:145], v[214:217], v[84:87]
	v_mfma_f32_16x16x32_bf16 v[80:83], v[150:153], v[214:217], v[80:83]
	v_mfma_f32_16x16x32_bf16 v[68:71], v[142:145], v[222:225], v[68:71]
	v_mfma_f32_16x16x32_bf16 v[64:67], v[150:153], v[222:225], v[64:67]
	v_mfma_f32_16x16x32_bf16 v[24:27], v[142:145], v[234:237], v[24:27]
	v_mfma_f32_16x16x32_bf16 v[20:23], v[150:153], v[234:237], v[20:23]
	s_setprio 0
	s_setprio 1
	v_mfma_f32_16x16x32_bf16 v[76:79], v[154:157], v[198:201], v[76:79]
	v_mfma_f32_16x16x32_bf16 v[72:75], v[162:165], v[198:201], v[72:75]
	v_mfma_f32_16x16x32_bf16 v[60:63], v[154:157], v[210:213], v[60:63]
	v_mfma_f32_16x16x32_bf16 v[56:59], v[162:165], v[210:213], v[56:59]
	v_mfma_f32_16x16x32_bf16 v[52:55], v[154:157], v[218:221], v[52:55]
	v_mfma_f32_16x16x32_bf16 v[48:51], v[162:165], v[218:221], v[48:51]
	v_mfma_f32_16x16x32_bf16 v[44:47], v[154:157], v[230:233], v[44:47]
	v_mfma_f32_16x16x32_bf16 v[0:3], v[162:165], v[230:233], v[0:3]
	v_mfma_f32_16x16x32_bf16 v[76:79], v[158:161], v[202:205], v[76:79]
	v_mfma_f32_16x16x32_bf16 v[72:75], v[182:185], v[202:205], v[72:75]
	v_mfma_f32_16x16x32_bf16 v[60:63], v[158:161], v[214:217], v[60:63]
	v_mfma_f32_16x16x32_bf16 v[56:59], v[182:185], v[214:217], v[56:59]
	v_mfma_f32_16x16x32_bf16 v[52:55], v[158:161], v[222:225], v[52:55]
	v_mfma_f32_16x16x32_bf16 v[48:51], v[182:185], v[222:225], v[48:51]
	v_mfma_f32_16x16x32_bf16 v[44:47], v[158:161], v[234:237], v[44:47]
	v_mfma_f32_16x16x32_bf16 v[0:3], v[182:185], v[234:237], v[0:3]
	s_setprio 0
	s_barrier
	s_add_i32 s86, s86, 2
	s_add_u32 s56, s56, 0x100
	s_addc_u32 s57, s57, 0
	s_add_u32 s84, s84, 0x100
	s_addc_u32 s85, s85, 0
	s_cmp_gt_u32 s86, 13
	s_cbranch_scc0 .LBB0_1258
	s_and_b64 vcc, exec, s[16:17]
	s_cbranch_vccz .LBB0_1261
	s_barrier

.LBB0_1388:
	ds_read_b128 v[128:131], v173
	ds_read_b128 v[132:135], v173 offset:1024
	ds_read_b128 v[136:139], v173 offset:2048
	ds_read_b128 v[140:143], v173 offset:3072
	ds_read_b128 v[144:147], v174
	ds_read_b128 v[148:151], v174 offset:1024
	ds_read_b128 v[152:155], v174 offset:2048
	ds_read_b128 v[156:159], v174 offset:3072
	s_add_u32 s10, s8, 0x100
	s_addc_u32 s11, s9, 0
	s_cmp_eq_u32 s42, 40
	s_cselect_b32 s15, s7, s11
	s_cselect_b32 s14, s6, s10
	s_cselect_b32 s13, s1, s41
	s_cselect_b32 s12, s0, s40
	v_lshl_add_u64 v[208:209], s[8:9], 0, v[168:169]
	s_add_i32 m0, s22, 0xc000
	ds_read_b128 v[176:179], v175
	ds_read_b128 v[180:183], v175 offset:1024
	ds_read_b128 v[184:187], v175 offset:2048
	ds_read_b128 v[188:191], v175 offset:3072
	ds_read_b128 v[192:195], v175 offset:4096
	ds_read_b128 v[196:199], v175 offset:5120
	ds_read_b128 v[200:203], v175 offset:6144
	ds_read_b128 v[204:207], v175 offset:7168
	global_load_lds_dwordx4 v[208:209], off
	v_lshl_add_u64 v[208:209], s[8:9], 0, v[170:171]
	s_add_i32 m0, s22, 0xe000
	s_nop 0
	global_load_lds_dwordx4 v[208:209], off
	s_waitcnt vmcnt(8)
	s_waitcnt lgkmcnt(0)
	s_barrier
	s_setprio 1
	s_waitcnt lgkmcnt(0)
	v_mfma_f32_16x16x32_bf16 v[124:127], v[128:131], v[176:179], v[124:127]
	v_mfma_f32_16x16x32_bf16 v[120:123], v[136:139], v[176:179], v[120:123]
	v_mfma_f32_16x16x32_bf16 v[116:119], v[128:131], v[184:187], v[116:119]
	v_mfma_f32_16x16x32_bf16 v[112:115], v[136:139], v[184:187], v[112:115]
	v_mfma_f32_16x16x32_bf16 v[96:99], v[128:131], v[192:195], v[96:99]
	v_mfma_f32_16x16x32_bf16 v[88:91], v[136:139], v[192:195], v[88:91]
	v_mfma_f32_16x16x32_bf16 v[80:83], v[128:131], v[200:203], v[80:83]
	v_mfma_f32_16x16x32_bf16 v[72:75], v[136:139], v[200:203], v[72:75]
	v_mfma_f32_16x16x32_bf16 v[124:127], v[132:135], v[180:183], v[124:127]
	v_mfma_f32_16x16x32_bf16 v[120:123], v[140:143], v[180:183], v[120:123]
	v_mfma_f32_16x16x32_bf16 v[116:119], v[132:135], v[188:191], v[116:119]
	v_mfma_f32_16x16x32_bf16 v[112:115], v[140:143], v[188:191], v[112:115]
	v_mfma_f32_16x16x32_bf16 v[96:99], v[132:135], v[196:199], v[96:99]
	v_mfma_f32_16x16x32_bf16 v[88:91], v[140:143], v[196:199], v[88:91]
	v_mfma_f32_16x16x32_bf16 v[80:83], v[132:135], v[204:207], v[80:83]
	v_mfma_f32_16x16x32_bf16 v[72:75], v[140:143], v[204:207], v[72:75]
	s_setprio 0
	s_setprio 1
	v_mfma_f32_16x16x32_bf16 v[108:111], v[144:147], v[176:179], v[108:111]
	v_mfma_f32_16x16x32_bf16 v[104:107], v[152:155], v[176:179], v[104:107]
	v_mfma_f32_16x16x32_bf16 v[100:103], v[144:147], v[184:187], v[100:103]
	v_mfma_f32_16x16x32_bf16 v[92:95], v[152:155], v[184:187], v[92:95]
	v_mfma_f32_16x16x32_bf16 v[84:87], v[144:147], v[192:195], v[84:87]
	v_mfma_f32_16x16x32_bf16 v[76:79], v[152:155], v[192:195], v[76:79]
	v_mfma_f32_16x16x32_bf16 v[68:71], v[144:147], v[200:203], v[68:71]
	v_mfma_f32_16x16x32_bf16 v[64:67], v[152:155], v[200:203], v[64:67]
	v_mfma_f32_16x16x32_bf16 v[108:111], v[148:151], v[180:183], v[108:111]
	v_mfma_f32_16x16x32_bf16 v[104:107], v[156:159], v[180:183], v[104:107]
	v_mfma_f32_16x16x32_bf16 v[100:103], v[148:151], v[188:191], v[100:103]
	v_mfma_f32_16x16x32_bf16 v[92:95], v[156:159], v[188:191], v[92:95]
	v_mfma_f32_16x16x32_bf16 v[84:87], v[148:151], v[196:199], v[84:87]
	v_mfma_f32_16x16x32_bf16 v[76:79], v[156:159], v[196:199], v[76:79]
	v_mfma_f32_16x16x32_bf16 v[68:71], v[148:151], v[204:207], v[68:71]
	v_mfma_f32_16x16x32_bf16 v[64:67], v[156:159], v[204:207], v[64:67]
	s_setprio 0
	s_barrier
	s_add_i32 s8, s31, s17
	v_lshl_add_u64 v[208:209], s[12:13], 0, v[164:165]
	s_mov_b32 m0, s8
	ds_read_b128 v[176:179], v175 offset:16384
	ds_read_b128 v[180:183], v175 offset:17408
	ds_read_b128 v[184:187], v175 offset:18432
	ds_read_b128 v[188:191], v175 offset:19456
	ds_read_b128 v[192:195], v175 offset:20480
	ds_read_b128 v[196:199], v175 offset:21504
	ds_read_b128 v[200:203], v175 offset:22528
	ds_read_b128 v[204:207], v175 offset:23552
	global_load_lds_dwordx4 v[208:209], off
	s_add_i32 m0, s8, 0x2000
	s_add_u32 s8, s12, 0xb0000
	v_lshl_add_u64 v[210:211], s[12:13], 0, v[160:161]
	s_addc_u32 s9, s13, 0
	s_add_i32 s43, s34, s17
	global_load_lds_dwordx4 v[210:211], off
	s_mov_b32 m0, s43
	v_lshl_add_u64 v[214:215], s[14:15], 0, v[162:163]
	global_load_lds_dwordx4 v164, s[8:9]
	s_add_i32 m0, s43, 0x2000
	s_nop 0
	global_load_lds_dwordx4 v160, s[8:9]
	v_lshl_add_u64 v[212:213], s[14:15], 0, v[166:167]
	s_mov_b32 m0, s22
	s_nop 0
	global_load_lds_dwordx4 v[212:213], off
	s_mov_b32 m0, s23
	s_nop 0
	global_load_lds_dwordx4 v[214:215], off
	s_waitcnt vmcnt(8)
	s_waitcnt lgkmcnt(0)
	s_barrier
	s_setprio 1
	s_waitcnt lgkmcnt(0)
	v_mfma_f32_16x16x32_bf16 v[60:63], v[128:131], v[176:179], v[60:63]
	v_mfma_f32_16x16x32_bf16 v[56:59], v[136:139], v[176:179], v[56:59]
	v_mfma_f32_16x16x32_bf16 v[48:51], v[128:131], v[184:187], v[48:51]
	v_mfma_f32_16x16x32_bf16 v[40:43], v[136:139], v[184:187], v[40:43]
	v_mfma_f32_16x16x32_bf16 v[32:35], v[128:131], v[192:195], v[32:35]
	v_mfma_f32_16x16x32_bf16 v[24:27], v[136:139], v[192:195], v[24:27]
	v_mfma_f32_16x16x32_bf16 v[16:19], v[128:131], v[200:203], v[16:19]
	v_mfma_f32_16x16x32_bf16 v[8:11], v[136:139], v[200:203], v[8:11]
	v_mfma_f32_16x16x32_bf16 v[60:63], v[132:135], v[180:183], v[60:63]
	v_mfma_f32_16x16x32_bf16 v[56:59], v[140:143], v[180:183], v[56:59]
	v_mfma_f32_16x16x32_bf16 v[48:51], v[132:135], v[188:191], v[48:51]
	v_mfma_f32_16x16x32_bf16 v[40:43], v[140:143], v[188:191], v[40:43]
	v_mfma_f32_16x16x32_bf16 v[32:35], v[132:135], v[196:199], v[32:35]
	v_mfma_f32_16x16x32_bf16 v[24:27], v[140:143], v[196:199], v[24:27]
	v_mfma_f32_16x16x32_bf16 v[16:19], v[132:135], v[204:207], v[16:19]
	v_mfma_f32_16x16x32_bf16 v[8:11], v[140:143], v[204:207], v[8:11]
	s_setprio 0
	s_setprio 1
	v_mfma_f32_16x16x32_bf16 v[52:55], v[144:147], v[176:179], v[52:55]
	v_mfma_f32_16x16x32_bf16 v[44:47], v[152:155], v[176:179], v[44:47]
	v_mfma_f32_16x16x32_bf16 v[36:39], v[144:147], v[184:187], v[36:39]
	v_mfma_f32_16x16x32_bf16 v[28:31], v[152:155], v[184:187], v[28:31]
	v_mfma_f32_16x16x32_bf16 v[20:23], v[144:147], v[192:195], v[20:23]
	v_mfma_f32_16x16x32_bf16 v[12:15], v[152:155], v[192:195], v[12:15]
	v_mfma_f32_16x16x32_bf16 v[4:7], v[144:147], v[200:203], v[4:7]
	v_mfma_f32_16x16x32_bf16 v[0:3], v[152:155], v[200:203], v[0:3]
	v_mfma_f32_16x16x32_bf16 v[52:55], v[148:151], v[180:183], v[52:55]
	v_mfma_f32_16x16x32_bf16 v[44:47], v[156:159], v[180:183], v[44:47]
	v_mfma_f32_16x16x32_bf16 v[36:39], v[148:151], v[188:191], v[36:39]
	v_mfma_f32_16x16x32_bf16 v[28:31], v[156:159], v[188:191], v[28:31]
	v_mfma_f32_16x16x32_bf16 v[20:23], v[148:151], v[196:199], v[20:23]
	v_mfma_f32_16x16x32_bf16 v[12:15], v[156:159], v[196:199], v[12:15]
	v_mfma_f32_16x16x32_bf16 v[4:7], v[148:151], v[204:207], v[4:7]
	v_mfma_f32_16x16x32_bf16 v[0:3], v[156:159], v[204:207], v[0:3]
	s_setprio 0
	s_barrier
	s_add_i32 s43, 0, 0x18000
	s_add_i32 s44, 0, 0x1c000
	v_add_u32_e32 v140, s43, v172
	v_add_u32_e32 v156, s44, v172
	ds_read_b128 v[128:131], v140
	ds_read_b128 v[132:135], v140 offset:1024
	ds_read_b128 v[136:139], v140 offset:2048
	ds_read_b128 v[140:143], v140 offset:3072
	ds_read_b128 v[144:147], v156
	ds_read_b128 v[148:151], v156 offset:1024
	ds_read_b128 v[152:155], v156 offset:2048
	ds_read_b128 v[156:159], v156 offset:3072
	s_add_u32 s8, s14, 0xb0000
	s_addc_u32 s9, s15, 0
	s_mov_b32 m0, s24
	ds_read_b128 v[176:179], v175 offset:32768
	ds_read_b128 v[180:183], v175 offset:33792
	ds_read_b128 v[184:187], v175 offset:34816
	ds_read_b128 v[188:191], v175 offset:35840
	ds_read_b128 v[192:195], v175 offset:36864
	ds_read_b128 v[196:199], v175 offset:37888
	ds_read_b128 v[200:203], v175 offset:38912
	ds_read_b128 v[204:207], v175 offset:39936
	global_load_lds_dwordx4 v166, s[8:9]
	s_mov_b32 m0, s25
	s_nop 0
	global_load_lds_dwordx4 v162, s[8:9]
	s_waitcnt vmcnt(8)
	s_waitcnt lgkmcnt(0)
	s_barrier
	s_setprio 1
	s_waitcnt lgkmcnt(0)
	v_mfma_f32_16x16x32_bf16 v[124:127], v[128:131], v[176:179], v[124:127]
	v_mfma_f32_16x16x32_bf16 v[120:123], v[136:139], v[176:179], v[120:123]
	v_mfma_f32_16x16x32_bf16 v[116:119], v[128:131], v[184:187], v[116:119]
	v_mfma_f32_16x16x32_bf16 v[112:115], v[136:139], v[184:187], v[112:115]
	v_mfma_f32_16x16x32_bf16 v[96:99], v[128:131], v[192:195], v[96:99]
	v_mfma_f32_16x16x32_bf16 v[88:91], v[136:139], v[192:195], v[88:91]
	v_mfma_f32_16x16x32_bf16 v[80:83], v[128:131], v[200:203], v[80:83]
	v_mfma_f32_16x16x32_bf16 v[72:75], v[136:139], v[200:203], v[72:75]
	v_mfma_f32_16x16x32_bf16 v[124:127], v[132:135], v[180:183], v[124:127]
	v_mfma_f32_16x16x32_bf16 v[120:123], v[140:143], v[180:183], v[120:123]
	v_mfma_f32_16x16x32_bf16 v[116:119], v[132:135], v[188:191], v[116:119]
	v_mfma_f32_16x16x32_bf16 v[112:115], v[140:143], v[188:191], v[112:115]
	v_mfma_f32_16x16x32_bf16 v[96:99], v[132:135], v[196:199], v[96:99]
	v_mfma_f32_16x16x32_bf16 v[88:91], v[140:143], v[196:199], v[88:91]
	v_mfma_f32_16x16x32_bf16 v[80:83], v[132:135], v[204:207], v[80:83]
	v_mfma_f32_16x16x32_bf16 v[72:75], v[140:143], v[204:207], v[72:75]
	s_setprio 0
	s_setprio 1
	v_mfma_f32_16x16x32_bf16 v[108:111], v[144:147], v[176:179], v[108:111]
	v_mfma_f32_16x16x32_bf16 v[104:107], v[152:155], v[176:179], v[104:107]
	v_mfma_f32_16x16x32_bf16 v[100:103], v[144:147], v[184:187], v[100:103]
	v_mfma_f32_16x16x32_bf16 v[92:95], v[152:155], v[184:187], v[92:95]
	v_mfma_f32_16x16x32_bf16 v[84:87], v[144:147], v[192:195], v[84:87]
	v_mfma_f32_16x16x32_bf16 v[76:79], v[152:155], v[192:195], v[76:79]
	v_mfma_f32_16x16x32_bf16 v[68:71], v[144:147], v[200:203], v[68:71]
	v_mfma_f32_16x16x32_bf16 v[64:67], v[152:155], v[200:203], v[64:67]
	v_mfma_f32_16x16x32_bf16 v[108:111], v[148:151], v[180:183], v[108:111]
	v_mfma_f32_16x16x32_bf16 v[104:107], v[156:159], v[180:183], v[104:107]
	v_mfma_f32_16x16x32_bf16 v[100:103], v[148:151], v[188:191], v[100:103]
	v_mfma_f32_16x16x32_bf16 v[92:95], v[156:159], v[188:191], v[92:95]
	v_mfma_f32_16x16x32_bf16 v[84:87], v[148:151], v[196:199], v[84:87]
	v_mfma_f32_16x16x32_bf16 v[76:79], v[156:159], v[196:199], v[76:79]
	v_mfma_f32_16x16x32_bf16 v[68:71], v[148:151], v[204:207], v[68:71]
	v_mfma_f32_16x16x32_bf16 v[64:67], v[156:159], v[204:207], v[64:67]
	s_setprio 0
	s_barrier
	s_add_i32 s8, s43, s17
	v_lshl_add_u64 v[208:209], v[208:209], 0, s[2:3]
	s_mov_b32 m0, s8
	ds_read_b128 v[176:179], v175 offset:49152
	ds_read_b128 v[180:183], v175 offset:50176
	ds_read_b128 v[184:187], v175 offset:51200
	ds_read_b128 v[188:191], v175 offset:52224
	ds_read_b128 v[192:195], v175 offset:53248
	ds_read_b128 v[196:199], v175 offset:54272
	ds_read_b128 v[200:203], v175 offset:55296
	ds_read_b128 v[204:207], v175 offset:56320
	global_load_lds_dwordx4 v[208:209], off
	s_add_i32 m0, s8, 0x2000
	s_add_u32 s8, s12, 0xb0080
	v_lshl_add_u64 v[208:209], v[210:211], 0, s[2:3]
	s_addc_u32 s9, s13, 0
	s_add_i32 s12, s44, s17
	global_load_lds_dwordx4 v[208:209], off
	s_mov_b32 m0, s12
	s_nop 0
	global_load_lds_dwordx4 v164, s[8:9]
	s_add_i32 m0, s12, 0x2000
	s_nop 0
	global_load_lds_dwordx4 v160, s[8:9]
	v_lshl_add_u64 v[208:209], v[212:213], 0, s[2:3]
	s_mov_b32 m0, s29
	s_nop 0
	global_load_lds_dwordx4 v[208:209], off
	v_lshl_add_u64 v[208:209], v[214:215], 0, s[2:3]
	s_mov_b32 m0, s30
	s_nop 0
	global_load_lds_dwordx4 v[208:209], off
	s_waitcnt vmcnt(8)
	s_waitcnt lgkmcnt(0)
	s_barrier
	s_setprio 1
	s_waitcnt lgkmcnt(0)
	v_mfma_f32_16x16x32_bf16 v[60:63], v[128:131], v[176:179], v[60:63]
	v_mfma_f32_16x16x32_bf16 v[56:59], v[136:139], v[176:179], v[56:59]
	v_mfma_f32_16x16x32_bf16 v[48:51], v[128:131], v[184:187], v[48:51]
	v_mfma_f32_16x16x32_bf16 v[40:43], v[136:139], v[184:187], v[40:43]
	v_mfma_f32_16x16x32_bf16 v[32:35], v[128:131], v[192:195], v[32:35]
	v_mfma_f32_16x16x32_bf16 v[24:27], v[136:139], v[192:195], v[24:27]
	v_mfma_f32_16x16x32_bf16 v[16:19], v[128:131], v[200:203], v[16:19]
	v_mfma_f32_16x16x32_bf16 v[8:11], v[136:139], v[200:203], v[8:11]
	v_mfma_f32_16x16x32_bf16 v[60:63], v[132:135], v[180:183], v[60:63]
	v_mfma_f32_16x16x32_bf16 v[56:59], v[140:143], v[180:183], v[56:59]
	v_mfma_f32_16x16x32_bf16 v[48:51], v[132:135], v[188:191], v[48:51]
	v_mfma_f32_16x16x32_bf16 v[40:43], v[140:143], v[188:191], v[40:43]
	v_mfma_f32_16x16x32_bf16 v[32:35], v[132:135], v[196:199], v[32:35]
	v_mfma_f32_16x16x32_bf16 v[24:27], v[140:143], v[196:199], v[24:27]
	v_mfma_f32_16x16x32_bf16 v[16:19], v[132:135], v[204:207], v[16:19]
	v_mfma_f32_16x16x32_bf16 v[8:11], v[140:143], v[204:207], v[8:11]
	s_setprio 0
	s_setprio 1
	v_mfma_f32_16x16x32_bf16 v[52:55], v[144:147], v[176:179], v[52:55]
	v_mfma_f32_16x16x32_bf16 v[44:47], v[152:155], v[176:179], v[44:47]
	v_mfma_f32_16x16x32_bf16 v[36:39], v[144:147], v[184:187], v[36:39]
	v_mfma_f32_16x16x32_bf16 v[28:31], v[152:155], v[184:187], v[28:31]
	v_mfma_f32_16x16x32_bf16 v[20:23], v[144:147], v[192:195], v[20:23]
	v_mfma_f32_16x16x32_bf16 v[12:15], v[152:155], v[192:195], v[12:15]
	v_mfma_f32_16x16x32_bf16 v[4:7], v[144:147], v[200:203], v[4:7]
	v_mfma_f32_16x16x32_bf16 v[0:3], v[152:155], v[200:203], v[0:3]
	v_mfma_f32_16x16x32_bf16 v[52:55], v[148:151], v[180:183], v[52:55]
	v_mfma_f32_16x16x32_bf16 v[44:47], v[156:159], v[180:183], v[44:47]
	v_mfma_f32_16x16x32_bf16 v[36:39], v[148:151], v[188:191], v[36:39]
	v_mfma_f32_16x16x32_bf16 v[28:31], v[156:159], v[188:191], v[28:31]
	v_mfma_f32_16x16x32_bf16 v[20:23], v[148:151], v[196:199], v[20:23]
	v_mfma_f32_16x16x32_bf16 v[12:15], v[156:159], v[196:199], v[12:15]
	v_mfma_f32_16x16x32_bf16 v[4:7], v[148:151], v[204:207], v[4:7]
	v_mfma_f32_16x16x32_bf16 v[0:3], v[156:159], v[204:207], v[0:3]
	s_setprio 0
	s_barrier
	s_add_i32 s42, s42, 2
	s_add_u32 s40, s40, 0x100
	s_addc_u32 s41, s41, 0
	s_cmp_gt_u32 s42, 41
	s_mov_b64 s[8:9], s[10:11]
	s_cbranch_scc0 .LBB0_1388
	s_lshl_b32 s8, s39, 8
	v_mbcnt_lo_u32_b32 v128, -1, 0
	v_mbcnt_hi_u32_b32 v128, -1, v128
	s_add_i32 s8, s8, s27
	v_and_or_b32 v129, v128, 15, s8
	s_lshl_b32 s8, s38, 8
	v_ashrrev_i32_e32 v128, 1, v128
	v_lshlrev_b32_e32 v129, 10, v129
	s_or_b32 s8, s8, s28
	v_and_b32_e32 v128, -8, v128
	v_add3_u32 v128, s8, v128, v129
	v_lshlrev_b32_e32 v177, 1, v128
	global_load_dwordx4 v[178:181], v177, s[48:49]
	v_add_u32_e32 v129, 0x100, v177
	global_load_dwordx4 v[182:185], v129, s[48:49]
	v_add_u32_e32 v129, 0x8000, v177
	v_add_u32_e32 v210, 0x10000, v177
	global_load_dwordx4 v[186:189], v129, s[48:49]
	global_load_dwordx4 v[194:197], v210, s[48:49]
	v_add_u32_e32 v129, 0x8100, v177
	global_load_dwordx4 v[190:193], v129, s[48:49]
	v_lshlrev_b32_e32 v176, 2, v128
	v_add_u32_e32 v128, 0x10100, v177
	v_add_u32_e32 v129, 0x18000, v177
	v_add_u32_e32 v130, 0x18100, v177
	v_add_u32_e32 v131, 0x40000, v177
	v_add_u32_e32 v132, 0x40100, v177
	v_add_u32_e32 v133, 0x48000, v177
	v_add_u32_e32 v134, 0x48100, v177
	v_add_u32_e32 v135, 0x50000, v177
	v_add_u32_e32 v136, 0x50100, v177
	v_add_u32_e32 v211, 0x58000, v177
	v_add_u32_e32 v212, 0x58100, v177
	global_load_dwordx4 v[198:201], v128, s[48:49]
	global_load_dwordx4 v[202:205], v129, s[48:49]
	global_load_dwordx4 v[206:209], v130, s[48:49]
	global_load_dwordx4 v[156:159], v131, s[48:49]
	global_load_dwordx4 v[152:155], v132, s[48:49]
	global_load_dwordx4 v[148:151], v133, s[48:49]
	global_load_dwordx4 v[144:147], v134, s[48:49]
	global_load_dwordx4 v[140:143], v135, s[48:49]
	s_nop 0
	global_load_dwordx4 v[136:139], v136, s[48:49]
	s_nop 0
	global_load_dwordx4 v[132:135], v211, s[48:49]
	global_load_dwordx4 v[128:131], v212, s[48:49]
	v_add_u32_e32 v177, v210, v177
	v_add_u32_e32 v216, 0x200, v176
	s_cmp_eq_u32 s26, s16
	s_mov_b32 s38, s36
	s_mov_b32 s39, s35
	s_mov_b64 s[10:11], s[0:1]
	s_mov_b64 s[8:9], s[6:7]
	s_waitcnt vmcnt(0)
	v_lshlrev_b32_e32 v210, 16, v178
	v_and_b32_e32 v211, 0xffff0000, v178
	v_lshlrev_b32_e32 v178, 16, v179
	v_and_b32_e32 v179, 0xffff0000, v179
	v_lshlrev_b32_e32 v212, 16, v180
	v_and_b32_e32 v213, 0xffff0000, v180
	v_lshlrev_b32_e32 v180, 16, v181
	v_and_b32_e32 v181, 0xffff0000, v181
	v_pk_add_f32 v[126:127], v[126:127], v[178:179]
	v_pk_add_f32 v[122:123], v[122:123], v[180:181]
	v_lshlrev_b32_e32 v178, 16, v182
	v_and_b32_e32 v179, 0xffff0000, v182
	v_lshlrev_b32_e32 v180, 16, v183
	v_and_b32_e32 v181, 0xffff0000, v183
	v_lshlrev_b32_e32 v182, 16, v184
	v_and_b32_e32 v183, 0xffff0000, v184
	v_pk_add_f32 v[124:125], v[124:125], v[210:211]
	v_pk_add_f32 v[120:121], v[120:121], v[212:213]
	v_lshlrev_b32_e32 v184, 16, v185
	v_and_b32_e32 v185, 0xffff0000, v185
	v_lshlrev_b32_e32 v210, 16, v186
	v_and_b32_e32 v211, 0xffff0000, v186
	v_lshlrev_b32_e32 v186, 16, v187
	v_and_b32_e32 v187, 0xffff0000, v187
	v_lshlrev_b32_e32 v212, 16, v188
	v_and_b32_e32 v213, 0xffff0000, v188
	v_lshlrev_b32_e32 v188, 16, v189
	v_and_b32_e32 v189, 0xffff0000, v189
	v_pk_add_f32 v[110:111], v[110:111], v[180:181]
	v_pk_add_f32 v[108:109], v[108:109], v[178:179]
	v_pk_add_f32 v[104:105], v[104:105], v[182:183]
	global_store_dwordx4 v176, v[124:127], s[4:5] nt
	global_store_dwordx4 v176, v[120:123], s[4:5] offset:16 nt
	v_pk_add_f32 v[106:107], v[106:107], v[184:185]
	v_pk_add_f32 v[118:119], v[118:119], v[186:187]
	v_pk_add_f32 v[116:117], v[116:117], v[210:211]
	v_pk_add_f32 v[114:115], v[114:115], v[188:189]
	v_pk_add_f32 v[112:113], v[112:113], v[212:213]
	global_store_dwordx4 v216, v[108:111], s[4:5] nt
	global_store_dwordx4 v216, v[104:107], s[4:5] offset:16 nt
	global_store_dwordx4 v177, v[116:119], s[4:5] nt
	global_store_dwordx4 v177, v[112:115], s[4:5] offset:16 nt
	v_lshlrev_b32_e32 v104, 16, v191
	v_and_b32_e32 v105, 0xffff0000, v191
	v_lshlrev_b32_e32 v214, 16, v190
	v_and_b32_e32 v215, 0xffff0000, v190
	v_pk_add_f32 v[102:103], v[102:103], v[104:105]
	v_lshlrev_b32_e32 v104, 16, v192
	v_and_b32_e32 v105, 0xffff0000, v192
	v_pk_add_f32 v[100:101], v[100:101], v[214:215]
	v_lshlrev_b32_e32 v106, 16, v193
	v_and_b32_e32 v107, 0xffff0000, v193
	v_pk_add_f32 v[92:93], v[92:93], v[104:105]
	v_add_u32_e32 v104, 0x10200, v176
	v_pk_add_f32 v[94:95], v[94:95], v[106:107]
	global_store_dwordx4 v104, v[100:103], s[4:5] nt
	global_store_dwordx4 v104, v[92:95], s[4:5] offset:16 nt
	s_nop 1
	v_lshlrev_b32_e32 v92, 16, v194
	v_and_b32_e32 v93, 0xffff0000, v194
	v_lshlrev_b32_e32 v94, 16, v195
	v_and_b32_e32 v95, 0xffff0000, v195
	v_pk_add_f32 v[92:93], v[96:97], v[92:93]
	v_lshlrev_b32_e32 v96, 16, v196
	v_and_b32_e32 v97, 0xffff0000, v196
	v_pk_add_f32 v[94:95], v[98:99], v[94:95]
	v_lshlrev_b32_e32 v98, 16, v197
	v_and_b32_e32 v99, 0xffff0000, v197
	v_pk_add_f32 v[88:89], v[88:89], v[96:97]
	v_add_u32_e32 v96, 0x20000, v176
	v_pk_add_f32 v[90:91], v[90:91], v[98:99]
	global_store_dwordx4 v96, v[92:95], s[4:5] nt
	global_store_dwordx4 v96, v[88:91], s[4:5] offset:16 nt
	s_nop 1
	v_lshlrev_b32_e32 v88, 16, v198
	v_and_b32_e32 v89, 0xffff0000, v198
	v_lshlrev_b32_e32 v90, 16, v199
	v_and_b32_e32 v91, 0xffff0000, v199
	v_pk_add_f32 v[84:85], v[84:85], v[88:89]
	v_lshlrev_b32_e32 v88, 16, v200
	v_and_b32_e32 v89, 0xffff0000, v200
	v_pk_add_f32 v[86:87], v[86:87], v[90:91]
	v_lshlrev_b32_e32 v90, 16, v201
	v_and_b32_e32 v91, 0xffff0000, v201
	v_pk_add_f32 v[76:77], v[76:77], v[88:89]
	v_add_u32_e32 v88, 0x20200, v176
	v_pk_add_f32 v[78:79], v[78:79], v[90:91]
	global_store_dwordx4 v88, v[84:87], s[4:5] nt
	global_store_dwordx4 v88, v[76:79], s[4:5] offset:16 nt
	s_nop 1
	v_lshlrev_b32_e32 v76, 16, v202
	v_and_b32_e32 v77, 0xffff0000, v202
	v_lshlrev_b32_e32 v78, 16, v203
	v_and_b32_e32 v79, 0xffff0000, v203
	v_pk_add_f32 v[76:77], v[80:81], v[76:77]
	v_lshlrev_b32_e32 v80, 16, v204
	v_and_b32_e32 v81, 0xffff0000, v204
	v_pk_add_f32 v[78:79], v[82:83], v[78:79]
	v_lshlrev_b32_e32 v82, 16, v205
	v_and_b32_e32 v83, 0xffff0000, v205
	v_pk_add_f32 v[72:73], v[72:73], v[80:81]
	v_add_u32_e32 v80, 0x30000, v176
	v_pk_add_f32 v[74:75], v[74:75], v[82:83]
	global_store_dwordx4 v80, v[76:79], s[4:5] nt
	global_store_dwordx4 v80, v[72:75], s[4:5] offset:16 nt
	s_nop 1
	v_lshlrev_b32_e32 v72, 16, v206
	v_and_b32_e32 v73, 0xffff0000, v206
	v_lshlrev_b32_e32 v74, 16, v207
	v_and_b32_e32 v75, 0xffff0000, v207
	v_pk_add_f32 v[68:69], v[68:69], v[72:73]
	v_lshlrev_b32_e32 v72, 16, v208
	v_and_b32_e32 v73, 0xffff0000, v208
	v_pk_add_f32 v[70:71], v[70:71], v[74:75]
	v_lshlrev_b32_e32 v74, 16, v209
	v_and_b32_e32 v75, 0xffff0000, v209
	v_pk_add_f32 v[64:65], v[64:65], v[72:73]
	v_add_u32_e32 v72, 0x30200, v176
	v_pk_add_f32 v[66:67], v[66:67], v[74:75]
	global_store_dwordx4 v72, v[68:71], s[4:5] nt
	global_store_dwordx4 v72, v[64:67], s[4:5] offset:16 nt
	s_nop 1
	v_lshlrev_b32_e32 v64, 16, v156
	v_and_b32_e32 v65, 0xffff0000, v156
	v_lshlrev_b32_e32 v66, 16, v157
	v_and_b32_e32 v67, 0xffff0000, v157
	v_pk_add_f32 v[60:61], v[60:61], v[64:65]
	v_lshlrev_b32_e32 v64, 16, v158
	v_and_b32_e32 v65, 0xffff0000, v158
	v_pk_add_f32 v[62:63], v[62:63], v[66:67]
	v_lshlrev_b32_e32 v66, 16, v159
	v_and_b32_e32 v67, 0xffff0000, v159
	v_pk_add_f32 v[56:57], v[56:57], v[64:65]
	v_add_u32_e32 v64, 0x80000, v176
	v_pk_add_f32 v[58:59], v[58:59], v[66:67]
	global_store_dwordx4 v64, v[60:63], s[4:5] nt
	global_store_dwordx4 v64, v[56:59], s[4:5] offset:16 nt
	s_nop 1
	v_lshlrev_b32_e32 v56, 16, v152
	v_and_b32_e32 v57, 0xffff0000, v152
	v_lshlrev_b32_e32 v58, 16, v153
	v_and_b32_e32 v59, 0xffff0000, v153
	v_pk_add_f32 v[52:53], v[52:53], v[56:57]
	v_lshlrev_b32_e32 v56, 16, v154
	v_and_b32_e32 v57, 0xffff0000, v154
	v_pk_add_f32 v[54:55], v[54:55], v[58:59]
	v_lshlrev_b32_e32 v58, 16, v155
	v_and_b32_e32 v59, 0xffff0000, v155
	v_pk_add_f32 v[44:45], v[44:45], v[56:57]
	v_add_u32_e32 v56, 0x80200, v176
	v_pk_add_f32 v[46:47], v[46:47], v[58:59]
	global_store_dwordx4 v56, v[52:55], s[4:5] nt
	global_store_dwordx4 v56, v[44:47], s[4:5] offset:16 nt
	s_nop 1
	v_lshlrev_b32_e32 v44, 16, v148
	v_and_b32_e32 v45, 0xffff0000, v148
	v_lshlrev_b32_e32 v46, 16, v149
	v_and_b32_e32 v47, 0xffff0000, v149
	v_pk_add_f32 v[44:45], v[48:49], v[44:45]
	v_lshlrev_b32_e32 v48, 16, v150
	v_and_b32_e32 v49, 0xffff0000, v150
	v_pk_add_f32 v[46:47], v[50:51], v[46:47]
	v_lshlrev_b32_e32 v50, 16, v151
	v_and_b32_e32 v51, 0xffff0000, v151
	v_pk_add_f32 v[40:41], v[40:41], v[48:49]
	v_add_u32_e32 v48, 0x90000, v176
	v_pk_add_f32 v[42:43], v[42:43], v[50:51]
	global_store_dwordx4 v48, v[44:47], s[4:5] nt
	global_store_dwordx4 v48, v[40:43], s[4:5] offset:16 nt
	s_nop 1
	v_lshlrev_b32_e32 v40, 16, v144
	v_and_b32_e32 v41, 0xffff0000, v144
	v_lshlrev_b32_e32 v42, 16, v145
	v_and_b32_e32 v43, 0xffff0000, v145
	v_pk_add_f32 v[36:37], v[36:37], v[40:41]
	v_lshlrev_b32_e32 v40, 16, v146
	v_and_b32_e32 v41, 0xffff0000, v146
	v_pk_add_f32 v[38:39], v[38:39], v[42:43]
	v_lshlrev_b32_e32 v42, 16, v147
	v_and_b32_e32 v43, 0xffff0000, v147
	v_pk_add_f32 v[28:29], v[28:29], v[40:41]
	v_add_u32_e32 v40, 0x90200, v176
	v_pk_add_f32 v[30:31], v[30:31], v[42:43]
	global_store_dwordx4 v40, v[36:39], s[4:5] nt
	global_store_dwordx4 v40, v[28:31], s[4:5] offset:16 nt
	s_nop 1
	v_lshlrev_b32_e32 v28, 16, v140
	v_and_b32_e32 v29, 0xffff0000, v140
	v_lshlrev_b32_e32 v30, 16, v141
	v_and_b32_e32 v31, 0xffff0000, v141
	v_pk_add_f32 v[28:29], v[32:33], v[28:29]
	v_lshlrev_b32_e32 v32, 16, v142
	v_and_b32_e32 v33, 0xffff0000, v142
	v_pk_add_f32 v[30:31], v[34:35], v[30:31]
	v_lshlrev_b32_e32 v34, 16, v143
	v_and_b32_e32 v35, 0xffff0000, v143
	v_pk_add_f32 v[24:25], v[24:25], v[32:33]
	v_add_u32_e32 v32, 0xa0000, v176
	v_pk_add_f32 v[26:27], v[26:27], v[34:35]
	global_store_dwordx4 v32, v[28:31], s[4:5] nt
	global_store_dwordx4 v32, v[24:27], s[4:5] offset:16 nt
	s_nop 1
	v_lshlrev_b32_e32 v24, 16, v136
	v_and_b32_e32 v25, 0xffff0000, v136
	v_lshlrev_b32_e32 v26, 16, v137
	v_and_b32_e32 v27, 0xffff0000, v137
	v_pk_add_f32 v[20:21], v[20:21], v[24:25]
	v_lshlrev_b32_e32 v24, 16, v138
	v_and_b32_e32 v25, 0xffff0000, v138
	v_pk_add_f32 v[22:23], v[22:23], v[26:27]
	v_lshlrev_b32_e32 v26, 16, v139
	v_and_b32_e32 v27, 0xffff0000, v139
	v_pk_add_f32 v[12:13], v[12:13], v[24:25]
	v_add_u32_e32 v24, 0xa0200, v176
	v_pk_add_f32 v[14:15], v[14:15], v[26:27]
	global_store_dwordx4 v24, v[20:23], s[4:5] nt
	global_store_dwordx4 v24, v[12:15], s[4:5] offset:16 nt
	s_nop 1
	v_lshlrev_b32_e32 v12, 16, v132
	v_and_b32_e32 v13, 0xffff0000, v132
	v_lshlrev_b32_e32 v14, 16, v133
	v_and_b32_e32 v15, 0xffff0000, v133
	v_pk_add_f32 v[12:13], v[16:17], v[12:13]
	v_lshlrev_b32_e32 v16, 16, v134
	v_and_b32_e32 v17, 0xffff0000, v134
	v_pk_add_f32 v[14:15], v[18:19], v[14:15]
	v_lshlrev_b32_e32 v18, 16, v135
	v_and_b32_e32 v19, 0xffff0000, v135
	v_pk_add_f32 v[8:9], v[8:9], v[16:17]
	v_add_u32_e32 v16, 0xb0000, v176
	v_pk_add_f32 v[10:11], v[10:11], v[18:19]
	global_store_dwordx4 v16, v[12:15], s[4:5] nt
	global_store_dwordx4 v16, v[8:11], s[4:5] offset:16 nt
	s_nop 1
	v_lshlrev_b32_e32 v8, 16, v128
	v_and_b32_e32 v9, 0xffff0000, v128
	v_lshlrev_b32_e32 v10, 16, v129
	v_and_b32_e32 v11, 0xffff0000, v129
	v_pk_add_f32 v[4:5], v[4:5], v[8:9]
	v_lshlrev_b32_e32 v8, 16, v130
	v_and_b32_e32 v9, 0xffff0000, v130
	v_pk_add_f32 v[6:7], v[6:7], v[10:11]
	v_lshlrev_b32_e32 v10, 16, v131
	v_and_b32_e32 v11, 0xffff0000, v131
	v_pk_add_f32 v[0:1], v[0:1], v[8:9]
	v_add_u32_e32 v8, 0xb0200, v176
	v_pk_add_f32 v[2:3], v[2:3], v[10:11]
	global_store_dwordx4 v8, v[4:7], s[4:5] nt
	global_store_dwordx4 v8, v[0:3], s[4:5] offset:16 nt
	s_cbranch_scc0 .LBB0_1381
	s_waitcnt vmcnt(0)
	s_cmpk_gt_u32 s33, 0xff
	s_cbranch_scc1 .LBB0_1392
	s_barrier
